# QK rms-norm+gain applied once in the in-proj epilogue from f32 accumulators (attention prologue/K staging become copies); attention epilogue gate loads hoisted, silu division via v_rcp
# speedup vs baseline: 1.0650x; 1.0132x over previous
.LBB0_202:
	v_mov_b32_e32 v3, v175
	v_and_b32_e32 v5, 64, v207
	v_lshlrev_b32_e32 v0, 3, v3
	v_and_b32_e32 v0, 56, v0
	v_lshlrev_b32_e32 v12, 2, v0
	v_lshlrev_b32_e32 v0, 1, v0
	v_lshl_add_u64 v[6:7], s[4:5], 0, v[0:1]
	v_xor_b32_e32 v0, 1, v207
	v_add_u32_e32 v180, 64, v5
	v_cmp_lt_i32_e32 vcc, v0, v180
	v_ashrrev_i32_e32 v4, 3, v3
	s_add_u32 s0, s11, s6
	v_cndmask_b32_e32 v0, v207, v0, vcc
	v_lshlrev_b32_e32 v181, 2, v0
	v_xor_b32_e32 v0, 2, v207
	v_cmp_lt_i32_e32 vcc, v0, v180
	v_ashrrev_i32_e32 v5, 31, v4
	s_addc_u32 s1, s8, s7
	v_cndmask_b32_e32 v0, v207, v0, vcc
	v_lshlrev_b32_e32 v182, 2, v0
	v_xor_b32_e32 v0, 4, v207
	v_cmp_lt_i32_e32 vcc, v0, v180
	v_lshl_add_u64 v[8:9], s[0:1], 0, v[4:5]
	v_mad_u64_u32 v[10:11], s[0:1], v8, s28, v[6:7]
	v_cndmask_b32_e32 v0, v207, v0, vcc
	v_lshlrev_b32_e32 v183, 2, v0
	v_mov_b32_e32 v0, v11
	v_mad_u64_u32 v[8:9], s[0:1], v9, s28, v[0:1]
	v_mov_b32_e32 v11, v8
	global_load_dwordx4 v[8:11], v[10:11], off
	v_lshrrev_b32_e32 v32, 1, v4
	v_bitop3_b32 v0, v32, 7, v3 bitop3:0x48
	v_lshlrev_b32_e32 v0, 4, v0
	v_lshl_or_b32 v0, v4, 7, v0
	s_add_i32 s0, s9, s6
	v_add_u32_e32 v3, s18, v0
	v_add_u32_e32 v0, s0, v4
	v_mad_i64_i32 v[4:5], s[0:1], v0, s28, v[6:7]
	s_add_u32 s6, s6, 64
	s_addc_u32 s7, s7, 0
	s_addk_i32 s18, 0x2000
	s_cmpk_eq_i32 s6, 0x100
	global_load_dwordx4 v[4:7], v[4:5], off
	s_waitcnt vmcnt(1)
	ds_write_b128 v3, v[8:11]
	s_waitcnt vmcnt(0)
	ds_write_b128 v3, v[4:7] offset:4096
	s_cbranch_scc0 .LBB0_202
	s_cmp_lt_i32 s13, 1
	s_mov_b64 s[6:7], -1
	s_waitcnt lgkmcnt(0)
	s_barrier
	s_cbranch_scc0 .LBB0_205
	s_lshl_b32 s0, s15, 8
	s_lshl_b32 s1, s13, 6
	s_sub_i32 s0, s0, s1
	s_addk_i32 s0, 0x4000
	s_mov_b64 s[6:7], 0

.LBB0_207:
	v_ashrrev_i32_e32 v184, 3, v2
	v_add_u32_e32 v3, s0, v184
	v_mov_b64_e32 v[4:5], s[92:93]
	v_mad_i64_i32 v[6:7], s[6:7], v3, s28, v[4:5]
	v_lshlrev_b32_e32 v0, 3, v2
	v_add_u32_e32 v3, 32, v3
	s_lshl_b32 s26, s3, 1
	v_and_b32_e32 v44, 56, v0
	v_mad_i64_i32 v[4:5], s[6:7], v3, s28, v[4:5]
	v_lshl_add_u64 v[6:7], v[6:7], 0, s[26:27]
	v_lshlrev_b32_e32 v0, 1, v44
	v_lshl_add_u64 v[4:5], v[4:5], 0, s[26:27]
	v_lshl_add_u64 v[6:7], v[6:7], 0, v[0:1]
	v_lshl_add_u64 v[4:5], v[4:5], 0, v[0:1]
	global_load_dwordx4 v[54:57], v[6:7], off offset:1024
	global_load_dwordx4 v[58:61], v[4:5], off offset:1024
	v_readlane_b32 s6, v250, 10
	v_ashrrev_i32_e32 v45, 2, v2
	v_readlane_b32 s7, v250, 11
	v_lshlrev_b32_e32 v3, 1, v2
	v_add_u32_e32 v6, s3, v45
	v_mov_b64_e32 v[4:5], s[6:7]
	s_ashr_i32 s1, s0, 31
	v_and_b32_e32 v75, 6, v3
	v_mad_i64_i32 v[166:167], s[6:7], v6, s19, v[4:5]
	v_mov_b32_e32 v7, v1
	v_lshlrev_b32_e32 v6, 4, v75
	v_lshl_add_u64 v[4:5], s[0:1], 1, v[166:167]
	v_lshl_add_u64 v[4:5], v[4:5], 0, v[6:7]
	global_load_dwordx4 v[62:65], v[4:5], off offset:16
	global_load_dwordx4 v[66:69], v[4:5], off
	v_lshrrev_b32_e32 v3, 1, v184
	v_and_b32_e32 v179, 15, v2
	v_bfe_u32 v178, v2, 4, 2
	v_xor_b32_e32 v2, v3, v2
	v_lshl_add_u32 v185, v44, 2, 0
	v_mov_b32_e32 v165, 0
	s_cmp_lt_i32 s13, -3
	v_mov_b32_e32 v164, 0
	v_mov_b32_e32 v163, 0
	v_mov_b32_e32 v162, 0
	v_mov_b32_e32 v85, 0
	v_mov_b32_e32 v84, v165
	v_mov_b32_e32 v83, v165
	v_mov_b32_e32 v82, v165
	v_mov_b32_e32 v81, 0
	v_mov_b32_e32 v80, v165
	v_mov_b32_e32 v79, v165
	v_mov_b32_e32 v78, v165
	v_mov_b32_e32 v73, 0
	v_mov_b32_e32 v72, v165
	v_mov_b32_e32 v71, v165
	v_mov_b32_e32 v70, v165
	v_mov_b32_e32 v53, 0
	v_mov_b32_e32 v52, v165
	v_mov_b32_e32 v51, v165
	v_mov_b32_e32 v50, v165
	v_mov_b32_e32 v49, 0
	v_mov_b32_e32 v48, v165
	v_mov_b32_e32 v47, v165
	v_mov_b32_e32 v46, v165
	v_mov_b32_e32 v44, v165
	v_lshlrev_b32_e32 v32, 3, v2
	v_lshlrev_b32_e32 v30, 6, v184
	v_and_or_b32 v186, v32, 56, v30
	v_or_b32_e32 v31, 1, v75
	v_mov_b32_e32 v43, v165
	v_mov_b32_e32 v42, v165
	v_mov_b32_e32 v41, 0
	v_mov_b32_e32 v40, v165
	v_mov_b32_e32 v39, v165
	v_mov_b32_e32 v38, v165
	v_mov_b32_e32 v37, 0
	v_mov_b32_e32 v36, v165
	v_mov_b32_e32 v35, v165
	v_mov_b32_e32 v34, v165
	v_lshl_add_u32 v29, v186, 1, 0
	s_waitcnt vmcnt(3)
	ds_write_b128 v29, v[54:57]
	s_waitcnt vmcnt(2)
	ds_write_b128 v29, v[58:61] offset:4096
	v_mov_b32_e32 v33, 0
	v_lshrrev_b32_e32 v3, 1, v45
	v_lshlrev_b32_e32 v2, 6, v45
	v_bitop3_b32 v4, v3, v75, 7 bitop3:0x6c
	v_bitop3_b32 v3, v3, v31, 7 bitop3:0x6c
	v_lshl_or_b32 v187, v4, 3, v2
	v_lshl_or_b32 v188, v3, 3, v2
	v_lshl_add_u32 v4, v187, 1, 0
	v_lshl_add_u32 v2, v188, 1, 0
	s_waitcnt vmcnt(0)
	ds_write_b128 v4, v[66:69] offset:16384
	ds_write_b128 v2, v[62:65] offset:16384
	v_mov_b32_e32 v45, 0
	v_mov_b32_e32 v32, v165
	v_mov_b32_e32 v31, v165
	v_mov_b32_e32 v30, v165
	v_mov_b32_e32 v29, 0
	v_mov_b32_e32 v28, v165
	v_mov_b32_e32 v27, v165
	v_mov_b32_e32 v26, v165
	v_mov_b32_e32 v25, 0
	v_mov_b32_e32 v24, v165
	v_mov_b32_e32 v23, v165
	v_mov_b32_e32 v22, v165
	v_mov_b32_e32 v21, 0
	v_mov_b32_e32 v20, v165
	v_mov_b32_e32 v19, v165
	v_mov_b32_e32 v18, v165
	v_mov_b32_e32 v17, 0
	v_mov_b32_e32 v16, v165
	v_mov_b32_e32 v15, v165
	v_mov_b32_e32 v14, v165
	v_mov_b32_e32 v13, 0
	v_mov_b32_e32 v12, v165
	v_mov_b32_e32 v11, v165
	v_mov_b32_e32 v10, v165
	v_mov_b32_e32 v9, 0
	v_mov_b32_e32 v8, v165
	v_mov_b32_e32 v7, v165
	v_mov_b32_e32 v6, v165
	v_mov_b32_e32 v5, 0
	v_mov_b32_e32 v4, v165
	v_mov_b32_e32 v3, v165
	v_mov_b32_e32 v2, v165
	s_waitcnt lgkmcnt(0)
	s_barrier
	s_cbranch_scc1 .LBB0_225
	s_lshl_b32 s1, s16, 13
	s_add_i32 s16, s1, 0
	v_lshl_add_u64 v[168:169], s[4:5], 0, v[0:1]
	s_mul_i32 s1, s14, 0x7c
	s_mul_i32 s4, s17, 0x7c
	s_sub_i32 s1, s1, s4
	s_add_i32 s1, s1, 0
	s_lshl_b32 s0, s15, 8
	s_add_i32 s17, s1, 0xa360
	s_lshl_b32 s1, s13, 6
	v_lshlrev_b32_e32 v3, 3, v75
	v_xor_b32_e32 v74, 0x80000000, v74
	s_sub_i32 s0, s0, s1
	v_mov_b32_e32 v162, v1
	v_mov_b32_e32 v163, v1
	v_mov_b32_e32 v2, 0
	s_add_i32 s8, s13, 4
	s_lshl_b32 s9, s15, 11
	s_add_i32 s15, s12, 7
	v_mov_b32_e32 v75, v74
	v_mov_b32_e32 v76, v74
	v_mov_b32_e32 v77, v74
	s_add_i32 s18, s0, 0x4040
	s_mov_b32 s19, 0
	v_lshlrev_b32_e32 v0, 1, v3
	s_mov_b32 s21, 0
	v_mov_b64_e32 v[164:165], v[162:163]
	v_mov_b32_e32 v3, v2
	v_mov_b32_e32 v4, v2
	v_mov_b32_e32 v5, v2
	v_mov_b32_e32 v6, v2
	v_mov_b32_e32 v7, v2
	v_mov_b32_e32 v8, v2
	v_mov_b32_e32 v9, v2
	v_mov_b32_e32 v10, v2
	v_mov_b32_e32 v11, v2
	v_mov_b32_e32 v12, v2
	v_mov_b32_e32 v13, v2
	v_mov_b32_e32 v14, v2
	v_mov_b32_e32 v15, v2
	v_mov_b32_e32 v16, v2
	v_mov_b32_e32 v17, v2
	v_mov_b32_e32 v18, v2
	v_mov_b32_e32 v19, v2
	v_mov_b32_e32 v20, v2
	v_mov_b32_e32 v21, v2
	v_mov_b32_e32 v22, v2
	v_mov_b32_e32 v23, v2
	v_mov_b32_e32 v24, v2
	v_mov_b32_e32 v25, v2
	v_mov_b32_e32 v26, v2
	v_mov_b32_e32 v27, v2
	v_mov_b32_e32 v28, v2
	v_mov_b32_e32 v29, v2
	v_mov_b32_e32 v30, v2
	v_mov_b32_e32 v31, v2
	v_mov_b32_e32 v32, v2
	v_mov_b32_e32 v33, v2
	v_mov_b32_e32 v34, v2
	v_mov_b32_e32 v35, v2
	v_mov_b32_e32 v36, v2
	v_mov_b32_e32 v37, v2
	v_mov_b32_e32 v38, v2
	v_mov_b32_e32 v39, v2
	v_mov_b32_e32 v40, v2
	v_mov_b32_e32 v41, v2
	v_mov_b32_e32 v42, v2
	v_mov_b32_e32 v43, v2
	v_mov_b32_e32 v44, v2
	v_mov_b32_e32 v45, v2
	v_mov_b32_e32 v46, v2
	v_mov_b32_e32 v47, v2
	v_mov_b32_e32 v48, v2
	v_mov_b32_e32 v49, v2
	v_mov_b32_e32 v50, v2
	v_mov_b32_e32 v51, v2
	v_mov_b32_e32 v52, v2
	v_mov_b32_e32 v53, v2
	v_mov_b32_e32 v70, v2
	v_mov_b32_e32 v71, v2
	v_mov_b32_e32 v72, v2
	v_mov_b32_e32 v73, v2
	v_mov_b32_e32 v78, v2
	v_mov_b32_e32 v79, v2
	v_mov_b32_e32 v80, v2
	v_mov_b32_e32 v81, v2
	v_mov_b32_e32 v82, v2
	v_mov_b32_e32 v83, v2
	v_mov_b32_e32 v84, v2
	v_mov_b32_e32 v85, v2

.LBB0_221:
	s_andn2_b64 vcc, exec, s[0:1]
	s_cbranch_vccnz .LBB0_223
	s_add_i32 s4, s19, 0x1000
	s_and_b32 s0, s4, 0x1000
	s_lshl_b32 s0, s0, 1
	s_add_i32 s0, s0, 0
	v_lshl_add_u32 v113, v186, 1, s0
	s_waitcnt vmcnt(3)
	ds_write_b128 v113, v[54:57]
	s_waitcnt vmcnt(2)
	ds_write_b128 v113, v[58:61] offset:4096
	v_lshl_add_u32 v86, v187, 1, s0
	s_waitcnt vmcnt(0)
	ds_write_b128 v86, v[66:69] offset:16384
	v_lshl_add_u32 v86, v188, 1, s0
	ds_write_b128 v86, v[62:65] offset:16384

.LBB0_225:
	v_xor_b32_e32 v0, 16, v207
	v_cmp_lt_i32_e32 vcc, v0, v180
	s_add_u32 s0, s96, s26
	s_addc_u32 s1, s97, 0
	v_cndmask_b32_e32 v0, v207, v0, vcc
	s_waitcnt vmcnt(0)
	v_lshlrev_b32_e32 v66, 2, v0
	v_xor_b32_e32 v0, 32, v207
	v_cmp_lt_i32_e32 vcc, v0, v180
	s_andn2_b32 s10, s10, 63
	v_mov_b32_e32 v54, v179
	v_cndmask_b32_e32 v0, v207, v0, vcc
	v_lshlrev_b32_e32 v67, 2, v0
	ds_bpermute_b32 v0, v66, v165
	v_mov_b32_e32 v55, v178
	s_add_i32 s4, s11, s10
	v_add_u32_e32 v124, s4, v179
	v_mul_lo_u32 v124, v124, s28
	v_lshl_add_u32 v125, v178, 2, s3
	v_lshl_add_u32 v120, v125, 1, v124
	v_add_u32_e32 v121, 0x12000, v120
	v_add_u32_e32 v122, 0x24000, v120
	v_add_u32_e32 v123, 0x36000, v120
	global_load_dwordx2 v[88:89], v120, s[92:93] offset:2048
	global_load_dwordx2 v[90:91], v120, s[92:93] offset:2080
	global_load_dwordx2 v[92:93], v120, s[92:93] offset:2112
	global_load_dwordx2 v[94:95], v120, s[92:93] offset:2144
	global_load_dwordx2 v[96:97], v121, s[92:93] offset:2048
	global_load_dwordx2 v[98:99], v121, s[92:93] offset:2080
	global_load_dwordx2 v[100:101], v121, s[92:93] offset:2112
	global_load_dwordx2 v[102:103], v121, s[92:93] offset:2144
	global_load_dwordx2 v[104:105], v122, s[92:93] offset:2048
	global_load_dwordx2 v[106:107], v122, s[92:93] offset:2080
	global_load_dwordx2 v[108:109], v122, s[92:93] offset:2112
	global_load_dwordx2 v[110:111], v122, s[92:93] offset:2144
	global_load_dwordx2 v[112:113], v123, s[92:93] offset:2048
	global_load_dwordx2 v[114:115], v123, s[92:93] offset:2080
	global_load_dwordx2 v[116:117], v123, s[92:93] offset:2112
	global_load_dwordx2 v[118:119], v123, s[92:93] offset:2144
	v_mov_b64_e32 v[62:63], s[92:93]
	s_waitcnt lgkmcnt(0)
	v_add_f32_e32 v0, v165, v0
	ds_bpermute_b32 v56, v67, v0
	v_lshlrev_b32_e32 v69, 2, v55
	v_add_u32_e32 v64, s4, v54
	v_and_b32_e32 v68, 1, v55
	s_waitcnt lgkmcnt(0)
	v_add_f32_e32 v0, v0, v56
	v_add_u32_e32 v74, 12, v69
	v_ashrrev_i32_e32 v65, 31, v64
	v_rcp_f32_e32 v56, v0
	s_nop 0
	v_mov_b32_e32 v0, v56
	s_waitcnt vmcnt(0)
	v_mov_b32_e32 v54, v88
	v_mov_b32_e32 v55, v89
	v_pk_mul_f32 v[58:59], v[82:83], v[0:1] op_sel_hi:[1,0]
	v_pk_mul_f32 v[70:71], v[70:71], v[0:1] op_sel_hi:[1,0]
	v_pk_mul_f32 v[72:73], v[72:73], v[0:1] op_sel_hi:[1,0]
	v_pk_mul_f32 v[50:51], v[50:51], v[0:1] op_sel_hi:[1,0]
	v_pk_mul_f32 v[52:53], v[52:53], v[0:1] op_sel_hi:[1,0]
	s_mov_b64 s[34:35], -1
	s_nop 0
	v_lshlrev_b32_e32 v75, 16, v54
	v_and_b32_e32 v54, 0xffff0000, v54
	v_mul_f32_e32 v56, 0xbfb8aa3b, v75
	v_mul_f32_e32 v57, 0xbfb8aa3b, v54
	v_exp_f32_e32 v56, v56
	v_exp_f32_e32 v57, v57
	s_nop 0
	v_pk_add_f32 v[56:57], v[56:57], 1.0 op_sel_hi:[1,0]
	s_nop 0
	v_div_scale_f32 v76, s[6:7], v57, v57, v54
	v_rcp_f32_e32 v77, v76
	s_nop 0
	v_fma_f32 v82, -v76, v77, 1.0
	v_fmac_f32_e32 v77, v82, v77
	v_div_scale_f32 v82, vcc, v54, v57, v54
	v_mul_f32_e32 v83, v82, v77
	v_fma_f32 v86, -v76, v83, v82
	v_rcp_f32_e32 v76, v57
	s_nop 0
	v_mul_f32_e32 v57, v54, v76
	s_nop 0
	v_rcp_f32_e32 v54, v56
	s_nop 0
	v_mul_f32_e32 v56, v75, v54
	v_pk_mul_f32 v[56:57], v[58:59], v[56:57]
	v_lshlrev_b32_e32 v75, 16, v55
	v_and_b32_e32 v55, 0xffff0000, v55
	v_cvt_pk_bf16_f32 v54, v56, v57
	v_mul_f32_e32 v56, 0xbfb8aa3b, v75
	v_mul_f32_e32 v57, 0xbfb8aa3b, v55
	v_exp_f32_e32 v56, v56
	v_exp_f32_e32 v57, v57
	v_pk_mul_f32 v[58:59], v[84:85], v[0:1] op_sel_hi:[1,0]
	v_pk_add_f32 v[56:57], v[56:57], 1.0 op_sel_hi:[1,0]
	s_nop 0
	s_nop 0
	v_rcp_f32_e32 v76, v57
	s_nop 0
	v_mul_f32_e32 v57, v55, v76
	s_nop 0
	v_rcp_f32_e32 v55, v56
	s_nop 0
	v_mul_f32_e32 v56, v75, v55
	v_pk_mul_f32 v[56:57], v[58:59], v[56:57]
	v_pk_mul_f32 v[76:77], v[78:79], v[0:1] op_sel_hi:[1,0]
	v_cvt_pk_bf16_f32 v55, v56, v57
	v_mov_b32_e32 v56, v90
	v_mov_b32_e32 v57, v91
	s_nop 0
	v_lshlrev_b32_e32 v75, 16, v56
	v_and_b32_e32 v56, 0xffff0000, v56
	v_mul_f32_e32 v58, 0xbfb8aa3b, v75
	v_mul_f32_e32 v59, 0xbfb8aa3b, v56
	v_exp_f32_e32 v58, v58
	v_exp_f32_e32 v59, v59
	s_nop 0
	v_pk_add_f32 v[58:59], v[58:59], 1.0 op_sel_hi:[1,0]
	s_nop 0
	v_div_scale_f32 v78, s[6:7], v59, v59, v56
	v_rcp_f32_e32 v79, v78
	s_nop 0
	v_fma_f32 v82, -v78, v79, 1.0
	v_fmac_f32_e32 v79, v82, v79
	v_div_scale_f32 v82, vcc, v56, v59, v56
	v_mul_f32_e32 v83, v82, v79
	v_fma_f32 v84, -v78, v83, v82
	v_rcp_f32_e32 v78, v59
	s_nop 0
	v_mul_f32_e32 v59, v56, v78
	v_div_scale_f32 v56, s[6:7], v58, v58, v75
	v_rcp_f32_e32 v78, v56
	s_nop 0
	v_fma_f32 v79, -v56, v78, 1.0
	v_fmac_f32_e32 v78, v79, v78
	v_div_scale_f32 v79, vcc, v75, v58, v75
	v_mul_f32_e32 v82, v79, v78
	v_fma_f32 v83, -v56, v82, v79
	v_rcp_f32_e32 v56, v58
	s_nop 0
	v_mul_f32_e32 v58, v75, v56
	v_pk_mul_f32 v[58:59], v[76:77], v[58:59]
	v_lshlrev_b32_e32 v75, 16, v57
	v_and_b32_e32 v57, 0xffff0000, v57
	v_cvt_pk_bf16_f32 v56, v58, v59
	v_mul_f32_e32 v58, 0xbfb8aa3b, v75
	v_mul_f32_e32 v59, 0xbfb8aa3b, v57
	v_exp_f32_e32 v58, v58
	v_exp_f32_e32 v59, v59
	v_pk_mul_f32 v[76:77], v[80:81], v[0:1] op_sel_hi:[1,0]
	v_permlane16_swap_b32_e32 v54, v56
	v_pk_add_f32 v[58:59], v[58:59], 1.0 op_sel_hi:[1,0]
	s_nop 0
	s_nop 0
	v_rcp_f32_e32 v78, v59
	s_nop 0
	v_mul_f32_e32 v59, v57, v78
	s_nop 0
	v_rcp_f32_e32 v57, v58
	s_nop 0
	v_mul_f32_e32 v58, v75, v57
	v_pk_mul_f32 v[58:59], v[76:77], v[58:59]
	s_nop 0
	v_cvt_pk_bf16_f32 v57, v58, v59
	v_mov_b32_e32 v58, v92
	v_mov_b32_e32 v59, v93
	s_nop 0
	v_permlane16_swap_b32_e32 v55, v57
	v_mov_b32_e32 v60, v94
	v_mov_b32_e32 v61, v95
	s_nop 0
	v_lshlrev_b32_e32 v75, 16, v58
	v_and_b32_e32 v58, 0xffff0000, v58
	v_mul_f32_e32 v76, 0xbfb8aa3b, v75
	v_mul_f32_e32 v77, 0xbfb8aa3b, v58
	v_exp_f32_e32 v76, v76
	v_exp_f32_e32 v77, v77
	s_nop 0
	v_pk_add_f32 v[76:77], v[76:77], 1.0 op_sel_hi:[1,0]
	s_nop 0
	v_div_scale_f32 v78, s[6:7], v77, v77, v58
	v_rcp_f32_e32 v79, v78
	s_nop 0
	v_fma_f32 v80, -v78, v79, 1.0
	v_fmac_f32_e32 v79, v80, v79
	v_div_scale_f32 v80, vcc, v58, v77, v58
	v_mul_f32_e32 v81, v80, v79
	v_fma_f32 v82, -v78, v81, v80
	v_rcp_f32_e32 v78, v77
	s_nop 0
	v_mul_f32_e32 v77, v58, v78
	v_div_scale_f32 v58, s[6:7], v76, v76, v75
	v_rcp_f32_e32 v78, v58
	s_nop 0
	v_fma_f32 v79, -v58, v78, 1.0
	v_fmac_f32_e32 v78, v79, v78
	v_div_scale_f32 v79, vcc, v75, v76, v75
	v_mul_f32_e32 v80, v79, v78
	v_fma_f32 v81, -v58, v80, v79
	v_rcp_f32_e32 v58, v76
	s_nop 0
	v_mul_f32_e32 v76, v75, v58
	v_pk_mul_f32 v[70:71], v[70:71], v[76:77]
	v_lshlrev_b32_e32 v75, 16, v59
	v_and_b32_e32 v59, 0xffff0000, v59
	v_cvt_pk_bf16_f32 v58, v70, v71
	v_mul_f32_e32 v70, 0xbfb8aa3b, v75
	v_mul_f32_e32 v71, 0xbfb8aa3b, v59
	v_exp_f32_e32 v70, v70
	v_exp_f32_e32 v71, v71
	s_nop 0
	v_pk_add_f32 v[70:71], v[70:71], 1.0 op_sel_hi:[1,0]
	s_nop 0
	v_div_scale_f32 v76, s[6:7], v71, v71, v59
	v_rcp_f32_e32 v77, v76
	s_nop 0
	v_fma_f32 v78, -v76, v77, 1.0
	v_fmac_f32_e32 v77, v78, v77
	v_div_scale_f32 v78, vcc, v59, v71, v59
	v_mul_f32_e32 v79, v78, v77
	v_fma_f32 v80, -v76, v79, v78
	v_rcp_f32_e32 v76, v71
	s_nop 0
	v_mul_f32_e32 v71, v59, v76
	v_div_scale_f32 v59, s[6:7], v70, v70, v75
	v_rcp_f32_e32 v76, v59
	s_nop 0
	v_fma_f32 v77, -v59, v76, 1.0
	v_fmac_f32_e32 v76, v77, v76
	v_div_scale_f32 v77, vcc, v75, v70, v75
	v_mul_f32_e32 v78, v77, v76
	v_fma_f32 v79, -v59, v78, v77
	v_rcp_f32_e32 v59, v70
	s_nop 0
	v_mul_f32_e32 v70, v75, v59
	v_pk_mul_f32 v[70:71], v[72:73], v[70:71]
	s_nop 0
	v_lshlrev_b32_e32 v72, 16, v60
	v_and_b32_e32 v60, 0xffff0000, v60
	v_cvt_pk_bf16_f32 v59, v70, v71
	v_mul_f32_e32 v70, 0xbfb8aa3b, v72
	v_mul_f32_e32 v71, 0xbfb8aa3b, v60
	v_exp_f32_e32 v70, v70
	v_exp_f32_e32 v71, v71
	s_nop 0
	v_pk_add_f32 v[70:71], v[70:71], 1.0 op_sel_hi:[1,0]
	s_nop 0
	v_div_scale_f32 v73, s[6:7], v71, v71, v60
	v_rcp_f32_e32 v75, v73
	s_nop 0
	v_fma_f32 v76, -v73, v75, 1.0
	v_fmac_f32_e32 v75, v76, v75
	v_div_scale_f32 v76, vcc, v60, v71, v60
	v_mul_f32_e32 v77, v76, v75
	v_fma_f32 v78, -v73, v77, v76
	v_rcp_f32_e32 v73, v71
	s_nop 0
	v_mul_f32_e32 v71, v60, v73
	v_div_scale_f32 v60, s[6:7], v70, v70, v72
	v_rcp_f32_e32 v73, v60
	s_nop 0
	v_fma_f32 v75, -v60, v73, 1.0
	v_fmac_f32_e32 v73, v75, v73
	v_div_scale_f32 v75, vcc, v72, v70, v72
	v_mul_f32_e32 v76, v75, v73
	v_fma_f32 v77, -v60, v76, v75
	v_fmac_f32_e32 v76, v77, v73
	v_rcp_f32_e32 v60, v70
	s_nop 0
	v_mul_f32_e32 v70, v72, v60
	v_pk_mul_f32 v[50:51], v[50:51], v[70:71]
	v_lshlrev_b32_e32 v70, 16, v61
	v_and_b32_e32 v61, 0xffff0000, v61
	v_cvt_pk_bf16_f32 v60, v50, v51
	v_mul_f32_e32 v50, 0xbfb8aa3b, v70
	v_mul_f32_e32 v0, 0xbfb8aa3b, v61
	v_exp_f32_e32 v50, v50
	v_exp_f32_e32 v51, v0
	v_permlane16_swap_b32_e32 v58, v60
	v_pk_add_f32 v[50:51], v[50:51], 1.0 op_sel_hi:[1,0]
	s_nop 0
	v_div_scale_f32 v0, s[6:7], v51, v51, v61
	v_rcp_f32_e32 v71, v0
	s_nop 0
	v_fma_f32 v72, -v0, v71, 1.0
	v_fmac_f32_e32 v71, v72, v71
	v_div_scale_f32 v72, vcc, v61, v51, v61
	v_mul_f32_e32 v73, v72, v71
	v_fma_f32 v75, -v0, v73, v72
	v_rcp_f32_e32 v0, v51
	s_nop 0
	v_mul_f32_e32 v51, v61, v0
	v_div_scale_f32 v0, s[6:7], v50, v50, v70
	v_rcp_f32_e32 v61, v0
	s_nop 0
	v_fma_f32 v71, -v0, v61, 1.0
	v_fmac_f32_e32 v61, v71, v61
	v_div_scale_f32 v71, vcc, v70, v50, v70
	v_mul_f32_e32 v72, v71, v61
	v_fma_f32 v73, -v0, v72, v71
	v_fmac_f32_e32 v72, v73, v61
	v_rcp_f32_e32 v0, v50
	s_nop 0
	v_mul_f32_e32 v50, v70, v0
	ds_bpermute_b32 v0, v66, v164
	v_pk_mul_f32 v[50:51], v[52:53], v[50:51]
	v_cmp_eq_u32_e32 vcc, 0, v68
	v_cvt_pk_bf16_f32 v61, v50, v51
	v_lshlrev_b64 v[52:53], 11, v[64:65]
	v_cndmask_b32_e32 v50, v74, v69, vcc
	v_lshl_add_u64 v[52:53], s[0:1], 0, v[52:53]
	v_ashrrev_i32_e32 v51, 31, v50
	s_waitcnt lgkmcnt(0)
	v_add_f32_e32 v0, v164, v0
	v_lshl_add_u64 v[50:51], v[50:51], 1, v[52:53]
	ds_bpermute_b32 v52, v67, v0
	global_store_dwordx4 v[50:51], v[54:57], off
	v_permlane16_swap_b32_e32 v59, v61
	global_store_dwordx4 v[50:51], v[58:61], off offset:64
	s_waitcnt lgkmcnt(0)
	v_add_f32_e32 v0, v0, v52
	v_mov_b32_e32 v50, v179
	v_mov_b32_e32 v51, v178
	v_lshlrev_b32_e32 v55, 2, v51
	v_rcp_f32_e32 v52, v0
	s_nop 0
	v_mov_b32_e32 v0, v52
	v_add3_u32 v50, s4, 16, v50
	v_mov_b32_e32 v58, v96
	v_mov_b32_e32 v59, v97
	v_pk_mul_f32 v[46:47], v[46:47], v[0:1] op_sel_hi:[1,0]
	v_pk_mul_f32 v[48:49], v[48:49], v[0:1] op_sel_hi:[1,0]
	v_pk_mul_f32 v[42:43], v[42:43], v[0:1] op_sel_hi:[1,0]
	v_pk_mul_f32 v[44:45], v[44:45], v[0:1] op_sel_hi:[1,0]
	v_pk_mul_f32 v[38:39], v[38:39], v[0:1] op_sel_hi:[1,0]
	v_pk_mul_f32 v[40:41], v[40:41], v[0:1] op_sel_hi:[1,0]
	v_pk_mul_f32 v[34:35], v[34:35], v[0:1] op_sel_hi:[1,0]
	v_pk_mul_f32 v[36:37], v[36:37], v[0:1] op_sel_hi:[1,0]
	v_and_b32_e32 v54, 1, v51
	v_add_u32_e32 v56, 12, v55
	v_ashrrev_i32_e32 v51, 31, v50
	s_nop 0
	v_lshlrev_b32_e32 v57, 16, v58
	v_and_b32_e32 v58, 0xffff0000, v58
	v_mul_f32_e32 v60, 0xbfb8aa3b, v57
	v_mul_f32_e32 v61, 0xbfb8aa3b, v58
	v_exp_f32_e32 v60, v60
	v_exp_f32_e32 v61, v61
	s_nop 0
	v_pk_add_f32 v[60:61], v[60:61], 1.0 op_sel_hi:[1,0]
	s_nop 0
	v_div_scale_f32 v64, s[6:7], v61, v61, v58
	v_rcp_f32_e32 v65, v64
	s_nop 0
	v_fma_f32 v68, -v64, v65, 1.0
	v_fmac_f32_e32 v65, v68, v65
	v_div_scale_f32 v68, vcc, v58, v61, v58
	v_mul_f32_e32 v69, v68, v65
	v_fma_f32 v70, -v64, v69, v68
	v_rcp_f32_e32 v64, v61
	s_nop 0
	v_mul_f32_e32 v61, v58, v64
	v_div_scale_f32 v58, s[6:7], v60, v60, v57
	v_rcp_f32_e32 v64, v58
	s_nop 0
	v_fma_f32 v65, -v58, v64, 1.0
	v_fmac_f32_e32 v64, v65, v64
	v_div_scale_f32 v65, vcc, v57, v60, v57
	v_mul_f32_e32 v68, v65, v64
	v_fma_f32 v69, -v58, v68, v65
	v_rcp_f32_e32 v58, v60
	s_nop 0
	v_mul_f32_e32 v60, v57, v58
	v_pk_mul_f32 v[46:47], v[46:47], v[60:61]
	v_and_b32_e32 v57, 0xffff0000, v59
	v_cvt_pk_bf16_f32 v46, v46, v47
	v_lshlrev_b32_e32 v47, 16, v59
	v_mul_f32_e32 v58, 0xbfb8aa3b, v47
	v_mul_f32_e32 v59, 0xbfb8aa3b, v57
	v_exp_f32_e32 v58, v58
	v_exp_f32_e32 v59, v59
	s_nop 0
	v_pk_add_f32 v[58:59], v[58:59], 1.0 op_sel_hi:[1,0]
	s_nop 0
	s_nop 0
	v_rcp_f32_e32 v60, v59
	s_nop 0
	v_mul_f32_e32 v59, v57, v60
	s_nop 0
	v_rcp_f32_e32 v57, v58
	s_nop 0
	v_mul_f32_e32 v58, v47, v57
	v_pk_mul_f32 v[48:49], v[48:49], v[58:59]
	s_nop 0
	v_cvt_pk_bf16_f32 v47, v48, v49
	v_mov_b32_e32 v48, v98
	v_mov_b32_e32 v49, v99
	s_nop 0
	v_lshlrev_b32_e32 v57, 16, v48
	v_and_b32_e32 v48, 0xffff0000, v48
	v_mul_f32_e32 v58, 0xbfb8aa3b, v57
	v_mul_f32_e32 v59, 0xbfb8aa3b, v48
	v_exp_f32_e32 v58, v58
	v_exp_f32_e32 v59, v59
	s_nop 0
	v_pk_add_f32 v[58:59], v[58:59], 1.0 op_sel_hi:[1,0]
	s_nop 0
	v_div_scale_f32 v60, s[6:7], v59, v59, v48
	v_rcp_f32_e32 v61, v60
	s_nop 0
	v_fma_f32 v64, -v60, v61, 1.0
	v_fmac_f32_e32 v61, v64, v61
	v_div_scale_f32 v64, vcc, v48, v59, v48
	v_mul_f32_e32 v65, v64, v61
	v_fma_f32 v68, -v60, v65, v64
	v_rcp_f32_e32 v60, v59
	s_nop 0
	v_mul_f32_e32 v59, v48, v60
	v_div_scale_f32 v48, s[6:7], v58, v58, v57
	v_rcp_f32_e32 v60, v48
	s_nop 0
	v_fma_f32 v61, -v48, v60, 1.0
	v_fmac_f32_e32 v60, v61, v60
	v_div_scale_f32 v61, vcc, v57, v58, v57
	v_mul_f32_e32 v64, v61, v60
	v_fma_f32 v65, -v48, v64, v61
	v_rcp_f32_e32 v48, v58
	s_nop 0
	v_mul_f32_e32 v58, v57, v48
	v_pk_mul_f32 v[42:43], v[42:43], v[58:59]
	v_lshlrev_b32_e32 v57, 16, v49
	v_and_b32_e32 v49, 0xffff0000, v49
	v_cvt_pk_bf16_f32 v48, v42, v43
	v_mul_f32_e32 v42, 0xbfb8aa3b, v57
	v_mul_f32_e32 v43, 0xbfb8aa3b, v49
	v_exp_f32_e32 v42, v42
	v_exp_f32_e32 v43, v43
	v_permlane16_swap_b32_e32 v46, v48
	v_pk_add_f32 v[42:43], v[42:43], 1.0 op_sel_hi:[1,0]
	s_nop 0
	s_nop 0
	v_rcp_f32_e32 v58, v43
	s_nop 0
	v_mul_f32_e32 v43, v49, v58
	s_nop 0
	v_rcp_f32_e32 v49, v42
	s_nop 0
	v_mul_f32_e32 v42, v57, v49
	v_pk_mul_f32 v[42:43], v[44:45], v[42:43]
	s_nop 0
	v_cvt_pk_bf16_f32 v49, v42, v43
	v_mov_b32_e32 v42, v100
	v_mov_b32_e32 v43, v101
	s_nop 0
	v_permlane16_swap_b32_e32 v47, v49
	s_nop 0
	v_lshlrev_b32_e32 v57, 16, v42
	v_and_b32_e32 v42, 0xffff0000, v42
	v_mul_f32_e32 v44, 0xbfb8aa3b, v57
	v_mul_f32_e32 v45, 0xbfb8aa3b, v42
	v_exp_f32_e32 v44, v44
	v_exp_f32_e32 v45, v45
	s_nop 0
	v_pk_add_f32 v[44:45], v[44:45], 1.0 op_sel_hi:[1,0]
	s_nop 0
	v_div_scale_f32 v58, s[6:7], v45, v45, v42
	v_rcp_f32_e32 v59, v58
	s_nop 0
	v_fma_f32 v60, -v58, v59, 1.0
	v_fmac_f32_e32 v59, v60, v59
	v_div_scale_f32 v60, vcc, v42, v45, v42
	v_mul_f32_e32 v61, v60, v59
	v_fma_f32 v64, -v58, v61, v60
	v_rcp_f32_e32 v58, v45
	s_nop 0
	v_mul_f32_e32 v45, v42, v58
	v_div_scale_f32 v42, s[6:7], v44, v44, v57
	v_rcp_f32_e32 v58, v42
	s_nop 0
	v_fma_f32 v59, -v42, v58, 1.0
	v_fmac_f32_e32 v58, v59, v58
	v_div_scale_f32 v59, vcc, v57, v44, v57
	v_mul_f32_e32 v60, v59, v58
	v_fma_f32 v61, -v42, v60, v59
	v_rcp_f32_e32 v42, v44
	s_nop 0
	v_mul_f32_e32 v44, v57, v42
	v_pk_mul_f32 v[38:39], v[38:39], v[44:45]
	v_and_b32_e32 v44, 0xffff0000, v43
	v_cvt_pk_bf16_f32 v38, v38, v39
	v_lshlrev_b32_e32 v39, 16, v43
	v_mul_f32_e32 v42, 0xbfb8aa3b, v39
	v_mul_f32_e32 v43, 0xbfb8aa3b, v44
	v_exp_f32_e32 v42, v42
	v_exp_f32_e32 v43, v43
	s_nop 0
	v_pk_add_f32 v[42:43], v[42:43], 1.0 op_sel_hi:[1,0]
	s_nop 0
	v_div_scale_f32 v45, s[6:7], v43, v43, v44
	v_rcp_f32_e32 v57, v45
	s_nop 0
	v_fma_f32 v58, -v45, v57, 1.0
	v_fmac_f32_e32 v57, v58, v57
	v_div_scale_f32 v58, vcc, v44, v43, v44
	v_mul_f32_e32 v59, v58, v57
	v_fma_f32 v60, -v45, v59, v58
	v_rcp_f32_e32 v45, v43
	s_nop 0
	v_mul_f32_e32 v43, v44, v45
	v_div_scale_f32 v44, s[6:7], v42, v42, v39
	v_rcp_f32_e32 v45, v44
	s_nop 0
	v_fma_f32 v57, -v44, v45, 1.0
	v_fmac_f32_e32 v45, v57, v45
	v_div_scale_f32 v57, vcc, v39, v42, v39
	v_mul_f32_e32 v58, v57, v45
	v_fma_f32 v59, -v44, v58, v57
	v_rcp_f32_e32 v44, v42
	s_nop 0
	v_mul_f32_e32 v42, v39, v44
	v_pk_mul_f32 v[40:41], v[40:41], v[42:43]
	s_nop 0
	v_cvt_pk_bf16_f32 v39, v40, v41
	v_mov_b32_e32 v40, v102
	v_mov_b32_e32 v41, v103
	s_nop 0
	v_lshlrev_b32_e32 v44, 16, v40
	v_and_b32_e32 v40, 0xffff0000, v40
	v_mul_f32_e32 v42, 0xbfb8aa3b, v44
	v_mul_f32_e32 v43, 0xbfb8aa3b, v40
	v_exp_f32_e32 v42, v42
	v_exp_f32_e32 v43, v43
	s_nop 0
	v_pk_add_f32 v[42:43], v[42:43], 1.0 op_sel_hi:[1,0]
	s_nop 0
	v_div_scale_f32 v45, s[6:7], v43, v43, v40
	v_rcp_f32_e32 v52, v45
	s_nop 0
	v_fma_f32 v53, -v45, v52, 1.0
	v_fmac_f32_e32 v52, v53, v52
	v_div_scale_f32 v53, vcc, v40, v43, v40
	v_mul_f32_e32 v57, v53, v52
	v_fma_f32 v58, -v45, v57, v53
	v_rcp_f32_e32 v45, v43
	s_nop 0
	v_mul_f32_e32 v43, v40, v45
	v_div_scale_f32 v40, s[6:7], v42, v42, v44
	v_rcp_f32_e32 v45, v40
	s_nop 0
	v_fma_f32 v52, -v40, v45, 1.0
	v_fmac_f32_e32 v45, v52, v45
	v_div_scale_f32 v52, vcc, v44, v42, v44
	v_mul_f32_e32 v53, v52, v45
	v_fma_f32 v57, -v40, v53, v52
	v_fmac_f32_e32 v53, v57, v45
	v_rcp_f32_e32 v40, v42
	s_nop 0
	v_mul_f32_e32 v42, v44, v40
	v_pk_mul_f32 v[34:35], v[34:35], v[42:43]
	v_lshlrev_b32_e32 v42, 16, v41
	v_and_b32_e32 v41, 0xffff0000, v41
	v_cvt_pk_bf16_f32 v40, v34, v35
	v_mul_f32_e32 v34, 0xbfb8aa3b, v42
	v_mul_f32_e32 v0, 0xbfb8aa3b, v41
	v_exp_f32_e32 v34, v34
	v_exp_f32_e32 v35, v0
	v_permlane16_swap_b32_e32 v38, v40
	v_pk_add_f32 v[34:35], v[34:35], 1.0 op_sel_hi:[1,0]
	s_nop 0
	v_div_scale_f32 v0, s[6:7], v35, v35, v41
	v_rcp_f32_e32 v43, v0
	s_nop 0
	v_fma_f32 v44, -v0, v43, 1.0
	v_fmac_f32_e32 v43, v44, v43
	v_div_scale_f32 v44, vcc, v41, v35, v41
	v_mul_f32_e32 v45, v44, v43
	v_fma_f32 v52, -v0, v45, v44
	v_rcp_f32_e32 v0, v35
	s_nop 0
	v_mul_f32_e32 v35, v41, v0
	s_nop 0
	v_rcp_f32_e32 v0, v34
	s_nop 0
	v_mul_f32_e32 v34, v42, v0
	ds_bpermute_b32 v0, v66, v163
	v_pk_mul_f32 v[34:35], v[36:37], v[34:35]
	v_cmp_eq_u32_e32 vcc, 0, v54
	v_cvt_pk_bf16_f32 v41, v34, v35
	v_lshlrev_b64 v[36:37], 11, v[50:51]
	v_cndmask_b32_e32 v34, v56, v55, vcc
	v_lshl_add_u64 v[36:37], s[0:1], 0, v[36:37]
	v_ashrrev_i32_e32 v35, 31, v34
	s_waitcnt lgkmcnt(0)
	v_add_f32_e32 v0, v163, v0
	v_lshl_add_u64 v[34:35], v[34:35], 1, v[36:37]
	ds_bpermute_b32 v36, v67, v0
	v_permlane16_swap_b32_e32 v39, v41
	global_store_dwordx4 v[34:35], v[38:41], off offset:64
	global_store_dwordx4 v[34:35], v[46:49], off
	s_waitcnt lgkmcnt(0)
	v_add_f32_e32 v0, v0, v36
	v_mov_b32_e32 v34, v179
	v_mov_b32_e32 v35, v178
	v_lshlrev_b32_e32 v39, 2, v35
	v_rcp_f32_e32 v36, v0
	s_nop 0
	v_mov_b32_e32 v0, v36
	v_add3_u32 v34, s4, 32, v34
	v_mov_b32_e32 v42, v104
	v_mov_b32_e32 v43, v105
	v_pk_mul_f32 v[30:31], v[30:31], v[0:1] op_sel_hi:[1,0]
	v_pk_mul_f32 v[32:33], v[32:33], v[0:1] op_sel_hi:[1,0]
	v_pk_mul_f32 v[26:27], v[26:27], v[0:1] op_sel_hi:[1,0]
	v_pk_mul_f32 v[28:29], v[28:29], v[0:1] op_sel_hi:[1,0]
	v_pk_mul_f32 v[22:23], v[22:23], v[0:1] op_sel_hi:[1,0]
	v_pk_mul_f32 v[24:25], v[24:25], v[0:1] op_sel_hi:[1,0]
	v_pk_mul_f32 v[18:19], v[18:19], v[0:1] op_sel_hi:[1,0]
	v_pk_mul_f32 v[20:21], v[20:21], v[0:1] op_sel_hi:[1,0]
	v_and_b32_e32 v38, 1, v35
	v_add_u32_e32 v40, 12, v39
	v_ashrrev_i32_e32 v35, 31, v34
	s_nop 0
	v_lshlrev_b32_e32 v41, 16, v42
	v_and_b32_e32 v42, 0xffff0000, v42
	v_mul_f32_e32 v44, 0xbfb8aa3b, v41
	v_mul_f32_e32 v45, 0xbfb8aa3b, v42
	v_exp_f32_e32 v44, v44
	v_exp_f32_e32 v45, v45
	s_nop 0
	v_pk_add_f32 v[44:45], v[44:45], 1.0 op_sel_hi:[1,0]
	s_nop 0
	v_div_scale_f32 v46, s[6:7], v45, v45, v42
	v_rcp_f32_e32 v47, v46
	s_nop 0
	v_fma_f32 v48, -v46, v47, 1.0
	v_fmac_f32_e32 v47, v48, v47
	v_div_scale_f32 v48, vcc, v42, v45, v42
	v_mul_f32_e32 v49, v48, v47
	v_fma_f32 v50, -v46, v49, v48
	v_rcp_f32_e32 v46, v45
	s_nop 0
	v_mul_f32_e32 v45, v42, v46
	v_div_scale_f32 v42, s[6:7], v44, v44, v41
	v_rcp_f32_e32 v46, v42
	s_nop 0
	v_fma_f32 v47, -v42, v46, 1.0
	v_fmac_f32_e32 v46, v47, v46
	v_div_scale_f32 v47, vcc, v41, v44, v41
	v_mul_f32_e32 v48, v47, v46
	v_fma_f32 v49, -v42, v48, v47
	v_rcp_f32_e32 v42, v44
	s_nop 0
	v_mul_f32_e32 v44, v41, v42
	v_pk_mul_f32 v[30:31], v[30:31], v[44:45]
	v_and_b32_e32 v41, 0xffff0000, v43
	v_cvt_pk_bf16_f32 v30, v30, v31
	v_lshlrev_b32_e32 v31, 16, v43
	v_mul_f32_e32 v42, 0xbfb8aa3b, v31
	v_mul_f32_e32 v43, 0xbfb8aa3b, v41
	v_exp_f32_e32 v42, v42
	v_exp_f32_e32 v43, v43
	s_nop 0
	v_pk_add_f32 v[42:43], v[42:43], 1.0 op_sel_hi:[1,0]
	s_nop 0
	s_nop 0
	v_rcp_f32_e32 v44, v43
	s_nop 0
	v_mul_f32_e32 v43, v41, v44
	s_nop 0
	v_rcp_f32_e32 v41, v42
	s_nop 0
	v_mul_f32_e32 v42, v31, v41
	v_pk_mul_f32 v[32:33], v[32:33], v[42:43]
	s_nop 0
	v_cvt_pk_bf16_f32 v31, v32, v33
	v_mov_b32_e32 v32, v106
	v_mov_b32_e32 v33, v107
	s_nop 0
	v_lshlrev_b32_e32 v41, 16, v32
	v_and_b32_e32 v32, 0xffff0000, v32
	v_mul_f32_e32 v42, 0xbfb8aa3b, v41
	v_mul_f32_e32 v43, 0xbfb8aa3b, v32
	v_exp_f32_e32 v42, v42
	v_exp_f32_e32 v43, v43
	s_nop 0
	v_pk_add_f32 v[42:43], v[42:43], 1.0 op_sel_hi:[1,0]
	s_nop 0
	v_div_scale_f32 v44, s[6:7], v43, v43, v32
	v_rcp_f32_e32 v45, v44
	s_nop 0
	v_fma_f32 v46, -v44, v45, 1.0
	v_fmac_f32_e32 v45, v46, v45
	v_div_scale_f32 v46, vcc, v32, v43, v32
	v_mul_f32_e32 v47, v46, v45
	v_fma_f32 v48, -v44, v47, v46
	v_rcp_f32_e32 v44, v43
	s_nop 0
	v_mul_f32_e32 v43, v32, v44
	v_div_scale_f32 v32, s[6:7], v42, v42, v41
	v_rcp_f32_e32 v44, v32
	s_nop 0
	v_fma_f32 v45, -v32, v44, 1.0
	v_fmac_f32_e32 v44, v45, v44
	v_div_scale_f32 v45, vcc, v41, v42, v41
	v_mul_f32_e32 v46, v45, v44
	v_fma_f32 v47, -v32, v46, v45
	v_rcp_f32_e32 v32, v42
	s_nop 0
	v_mul_f32_e32 v42, v41, v32
	v_pk_mul_f32 v[26:27], v[26:27], v[42:43]
	v_lshlrev_b32_e32 v41, 16, v33
	v_and_b32_e32 v33, 0xffff0000, v33
	v_cvt_pk_bf16_f32 v32, v26, v27
	v_mul_f32_e32 v26, 0xbfb8aa3b, v41
	v_mul_f32_e32 v27, 0xbfb8aa3b, v33
	v_exp_f32_e32 v26, v26
	v_exp_f32_e32 v27, v27
	v_permlane16_swap_b32_e32 v30, v32
	v_pk_add_f32 v[26:27], v[26:27], 1.0 op_sel_hi:[1,0]
	s_nop 0
	s_nop 0
	v_rcp_f32_e32 v42, v27
	s_nop 0
	v_mul_f32_e32 v27, v33, v42
	s_nop 0
	v_rcp_f32_e32 v33, v26
	s_nop 0
	v_mul_f32_e32 v26, v41, v33
	v_pk_mul_f32 v[26:27], v[28:29], v[26:27]
	s_nop 0
	v_cvt_pk_bf16_f32 v33, v26, v27
	v_mov_b32_e32 v26, v108
	v_mov_b32_e32 v27, v109
	s_nop 0
	v_permlane16_swap_b32_e32 v31, v33
	s_nop 0
	v_lshlrev_b32_e32 v41, 16, v26
	v_and_b32_e32 v26, 0xffff0000, v26
	v_mul_f32_e32 v28, 0xbfb8aa3b, v41
	v_mul_f32_e32 v29, 0xbfb8aa3b, v26
	v_exp_f32_e32 v28, v28
	v_exp_f32_e32 v29, v29
	s_nop 0
	v_pk_add_f32 v[28:29], v[28:29], 1.0 op_sel_hi:[1,0]
	s_nop 0
	v_div_scale_f32 v42, s[6:7], v29, v29, v26
	v_rcp_f32_e32 v43, v42
	s_nop 0
	v_fma_f32 v44, -v42, v43, 1.0
	v_fmac_f32_e32 v43, v44, v43
	v_div_scale_f32 v44, vcc, v26, v29, v26
	v_mul_f32_e32 v45, v44, v43
	v_fma_f32 v46, -v42, v45, v44
	v_rcp_f32_e32 v42, v29
	s_nop 0
	v_mul_f32_e32 v29, v26, v42
	v_div_scale_f32 v26, s[6:7], v28, v28, v41
	v_rcp_f32_e32 v42, v26
	s_nop 0
	v_fma_f32 v43, -v26, v42, 1.0
	v_fmac_f32_e32 v42, v43, v42
	v_div_scale_f32 v43, vcc, v41, v28, v41
	v_mul_f32_e32 v44, v43, v42
	v_fma_f32 v45, -v26, v44, v43
	v_rcp_f32_e32 v26, v28
	s_nop 0
	v_mul_f32_e32 v28, v41, v26
	v_pk_mul_f32 v[22:23], v[22:23], v[28:29]
	v_and_b32_e32 v28, 0xffff0000, v27
	v_cvt_pk_bf16_f32 v22, v22, v23
	v_lshlrev_b32_e32 v23, 16, v27
	v_mul_f32_e32 v26, 0xbfb8aa3b, v23
	v_mul_f32_e32 v27, 0xbfb8aa3b, v28
	v_exp_f32_e32 v26, v26
	v_exp_f32_e32 v27, v27
	s_nop 0
	v_pk_add_f32 v[26:27], v[26:27], 1.0 op_sel_hi:[1,0]
	s_nop 0
	v_div_scale_f32 v29, s[6:7], v27, v27, v28
	v_rcp_f32_e32 v41, v29
	s_nop 0
	v_fma_f32 v42, -v29, v41, 1.0
	v_fmac_f32_e32 v41, v42, v41
	v_div_scale_f32 v42, vcc, v28, v27, v28
	v_mul_f32_e32 v43, v42, v41
	v_fma_f32 v44, -v29, v43, v42
	v_rcp_f32_e32 v29, v27
	s_nop 0
	v_mul_f32_e32 v27, v28, v29
	v_div_scale_f32 v28, s[6:7], v26, v26, v23
	v_rcp_f32_e32 v29, v28
	s_nop 0
	v_fma_f32 v41, -v28, v29, 1.0
	v_fmac_f32_e32 v29, v41, v29
	v_div_scale_f32 v41, vcc, v23, v26, v23
	v_mul_f32_e32 v42, v41, v29
	v_fma_f32 v43, -v28, v42, v41
	v_rcp_f32_e32 v28, v26
	s_nop 0
	v_mul_f32_e32 v26, v23, v28
	v_pk_mul_f32 v[24:25], v[24:25], v[26:27]
	s_nop 0
	v_cvt_pk_bf16_f32 v23, v24, v25
	v_mov_b32_e32 v24, v110
	v_mov_b32_e32 v25, v111
	s_nop 0
	v_lshlrev_b32_e32 v28, 16, v24
	v_and_b32_e32 v24, 0xffff0000, v24
	v_mul_f32_e32 v26, 0xbfb8aa3b, v28
	v_mul_f32_e32 v27, 0xbfb8aa3b, v24
	v_exp_f32_e32 v26, v26
	v_exp_f32_e32 v27, v27
	s_nop 0
	v_pk_add_f32 v[26:27], v[26:27], 1.0 op_sel_hi:[1,0]
	s_nop 0
	v_div_scale_f32 v29, s[6:7], v27, v27, v24
	v_rcp_f32_e32 v36, v29
	s_nop 0
	v_fma_f32 v37, -v29, v36, 1.0
	v_fmac_f32_e32 v36, v37, v36
	v_div_scale_f32 v37, vcc, v24, v27, v24
	v_mul_f32_e32 v41, v37, v36
	v_fma_f32 v42, -v29, v41, v37
	v_rcp_f32_e32 v29, v27
	s_nop 0
	v_mul_f32_e32 v27, v24, v29
	v_div_scale_f32 v24, s[6:7], v26, v26, v28
	v_rcp_f32_e32 v29, v24
	s_nop 0
	v_fma_f32 v36, -v24, v29, 1.0
	v_fmac_f32_e32 v29, v36, v29
	v_div_scale_f32 v36, vcc, v28, v26, v28
	v_mul_f32_e32 v37, v36, v29
	v_fma_f32 v41, -v24, v37, v36
	v_fmac_f32_e32 v37, v41, v29
	v_rcp_f32_e32 v24, v26
	s_nop 0
	v_mul_f32_e32 v26, v28, v24
	v_pk_mul_f32 v[18:19], v[18:19], v[26:27]
	v_lshlrev_b32_e32 v26, 16, v25
	v_and_b32_e32 v25, 0xffff0000, v25
	v_cvt_pk_bf16_f32 v24, v18, v19
	v_mul_f32_e32 v18, 0xbfb8aa3b, v26
	v_mul_f32_e32 v0, 0xbfb8aa3b, v25
	v_exp_f32_e32 v18, v18
	v_exp_f32_e32 v19, v0
	v_permlane16_swap_b32_e32 v22, v24
	v_pk_add_f32 v[18:19], v[18:19], 1.0 op_sel_hi:[1,0]
	s_nop 0
	v_div_scale_f32 v0, s[6:7], v19, v19, v25
	v_rcp_f32_e32 v27, v0
	s_nop 0
	v_fma_f32 v28, -v0, v27, 1.0
	v_fmac_f32_e32 v27, v28, v27
	v_div_scale_f32 v28, vcc, v25, v19, v25
	v_mul_f32_e32 v29, v28, v27
	v_fma_f32 v36, -v0, v29, v28
	v_rcp_f32_e32 v0, v19
	s_nop 0
	v_mul_f32_e32 v19, v25, v0
	s_nop 0
	v_rcp_f32_e32 v0, v18
	s_nop 0
	v_mul_f32_e32 v18, v26, v0
	ds_bpermute_b32 v0, v66, v162
	v_pk_mul_f32 v[18:19], v[20:21], v[18:19]
	v_cmp_eq_u32_e32 vcc, 0, v38
	v_cvt_pk_bf16_f32 v25, v18, v19
	v_lshlrev_b64 v[20:21], 11, v[34:35]
	v_cndmask_b32_e32 v18, v40, v39, vcc
	v_lshl_add_u64 v[20:21], s[0:1], 0, v[20:21]
	v_ashrrev_i32_e32 v19, 31, v18
	v_lshl_add_u64 v[18:19], v[18:19], 1, v[20:21]
	v_permlane16_swap_b32_e32 v23, v25
	s_waitcnt lgkmcnt(0)
	v_add_f32_e32 v0, v162, v0
	global_store_dwordx4 v[18:19], v[30:33], off
	global_store_dwordx4 v[18:19], v[22:25], off offset:64
	ds_bpermute_b32 v18, v67, v0
	s_waitcnt lgkmcnt(0)
	v_add_f32_e32 v0, v0, v18
	v_div_scale_f32 v18, s[6:7], v0, v0, 1.0
	v_lshlrev_b32_e32 v23, 2, v178
	v_add_u32_e32 v24, 12, v23
	v_rcp_f32_e32 v18, v0
	s_nop 0
	v_mov_b32_e32 v0, v18
	v_add3_u32 v18, s4, 48, v179
	v_mov_b32_e32 v26, v112
	v_mov_b32_e32 v27, v113
	v_pk_mul_f32 v[14:15], v[14:15], v[0:1] op_sel_hi:[1,0]
	v_pk_mul_f32 v[16:17], v[16:17], v[0:1] op_sel_hi:[1,0]
	v_pk_mul_f32 v[10:11], v[10:11], v[0:1] op_sel_hi:[1,0]
	v_pk_mul_f32 v[12:13], v[12:13], v[0:1] op_sel_hi:[1,0]
	v_pk_mul_f32 v[6:7], v[6:7], v[0:1] op_sel_hi:[1,0]
	v_pk_mul_f32 v[8:9], v[8:9], v[0:1] op_sel_hi:[1,0]
	v_pk_mul_f32 v[2:3], v[2:3], v[0:1] op_sel_hi:[1,0]
	v_pk_mul_f32 v[4:5], v[4:5], v[0:1] op_sel_hi:[1,0]
	v_and_b32_e32 v22, 1, v178
	v_ashrrev_i32_e32 v19, 31, v18
	s_nop 0
	v_lshlrev_b32_e32 v25, 16, v26
	v_and_b32_e32 v26, 0xffff0000, v26
	v_mul_f32_e32 v28, 0xbfb8aa3b, v25
	v_mul_f32_e32 v29, 0xbfb8aa3b, v26
	v_exp_f32_e32 v28, v28
	v_exp_f32_e32 v29, v29
	s_nop 0
	v_pk_add_f32 v[28:29], v[28:29], 1.0 op_sel_hi:[1,0]
	s_nop 0
	v_div_scale_f32 v30, s[4:5], v29, v29, v26
	v_rcp_f32_e32 v31, v30
	s_nop 0
	v_fma_f32 v32, -v30, v31, 1.0
	v_fmac_f32_e32 v31, v32, v31
	v_div_scale_f32 v32, vcc, v26, v29, v26
	v_mul_f32_e32 v33, v32, v31
	v_fma_f32 v34, -v30, v33, v32
	v_rcp_f32_e32 v30, v29
	s_nop 0
	v_mul_f32_e32 v29, v26, v30
	v_div_scale_f32 v26, s[4:5], v28, v28, v25
	v_rcp_f32_e32 v30, v26
	s_nop 0
	v_fma_f32 v31, -v26, v30, 1.0
	v_fmac_f32_e32 v30, v31, v30
	v_div_scale_f32 v31, vcc, v25, v28, v25
	v_mul_f32_e32 v32, v31, v30
	v_fma_f32 v33, -v26, v32, v31
	v_rcp_f32_e32 v26, v28
	s_nop 0
	v_mul_f32_e32 v28, v25, v26
	v_pk_mul_f32 v[14:15], v[14:15], v[28:29]
	v_and_b32_e32 v25, 0xffff0000, v27
	v_cvt_pk_bf16_f32 v14, v14, v15
	v_lshlrev_b32_e32 v15, 16, v27
	v_mul_f32_e32 v26, 0xbfb8aa3b, v15
	v_mul_f32_e32 v27, 0xbfb8aa3b, v25
	v_exp_f32_e32 v26, v26
	v_exp_f32_e32 v27, v27
	s_nop 0
	v_pk_add_f32 v[26:27], v[26:27], 1.0 op_sel_hi:[1,0]
	s_nop 0
	s_nop 0
	v_rcp_f32_e32 v28, v27
	s_nop 0
	v_mul_f32_e32 v27, v25, v28
	s_nop 0
	v_rcp_f32_e32 v25, v26
	s_nop 0
	v_mul_f32_e32 v26, v15, v25
	v_pk_mul_f32 v[16:17], v[16:17], v[26:27]
	s_nop 0
	v_cvt_pk_bf16_f32 v15, v16, v17
	v_mov_b32_e32 v16, v114
	v_mov_b32_e32 v17, v115
	s_nop 0
	v_lshlrev_b32_e32 v25, 16, v16
	v_and_b32_e32 v16, 0xffff0000, v16
	v_mul_f32_e32 v26, 0xbfb8aa3b, v25
	v_mul_f32_e32 v27, 0xbfb8aa3b, v16
	v_exp_f32_e32 v26, v26
	v_exp_f32_e32 v27, v27
	s_nop 0
	v_pk_add_f32 v[26:27], v[26:27], 1.0 op_sel_hi:[1,0]
	s_nop 0
	v_div_scale_f32 v28, s[4:5], v27, v27, v16
	v_rcp_f32_e32 v29, v28
	s_nop 0
	v_fma_f32 v30, -v28, v29, 1.0
	v_fmac_f32_e32 v29, v30, v29
	v_div_scale_f32 v30, vcc, v16, v27, v16
	v_mul_f32_e32 v31, v30, v29
	v_fma_f32 v32, -v28, v31, v30
	v_rcp_f32_e32 v28, v27
	s_nop 0
	v_mul_f32_e32 v27, v16, v28
	v_div_scale_f32 v16, s[4:5], v26, v26, v25
	v_rcp_f32_e32 v28, v16
	s_nop 0
	v_fma_f32 v29, -v16, v28, 1.0
	v_fmac_f32_e32 v28, v29, v28
	v_div_scale_f32 v29, vcc, v25, v26, v25
	v_mul_f32_e32 v30, v29, v28
	v_fma_f32 v31, -v16, v30, v29
	v_rcp_f32_e32 v16, v26
	s_nop 0
	v_mul_f32_e32 v26, v25, v16
	v_pk_mul_f32 v[10:11], v[10:11], v[26:27]
	v_lshlrev_b32_e32 v25, 16, v17
	v_and_b32_e32 v17, 0xffff0000, v17
	v_cvt_pk_bf16_f32 v16, v10, v11
	v_mul_f32_e32 v10, 0xbfb8aa3b, v25
	v_mul_f32_e32 v11, 0xbfb8aa3b, v17
	v_exp_f32_e32 v10, v10
	v_exp_f32_e32 v11, v11
	v_permlane16_swap_b32_e32 v14, v16
	v_pk_add_f32 v[10:11], v[10:11], 1.0 op_sel_hi:[1,0]
	s_nop 0
	s_nop 0
	v_rcp_f32_e32 v26, v11
	s_nop 0
	v_mul_f32_e32 v11, v17, v26
	s_nop 0
	v_rcp_f32_e32 v17, v10
	s_nop 0
	v_mul_f32_e32 v10, v25, v17
	v_pk_mul_f32 v[10:11], v[12:13], v[10:11]
	s_nop 0
	v_cvt_pk_bf16_f32 v17, v10, v11
	v_mov_b32_e32 v10, v116
	v_mov_b32_e32 v11, v117
	s_nop 0
	v_permlane16_swap_b32_e32 v15, v17
	s_nop 0
	v_lshlrev_b32_e32 v25, 16, v10
	v_and_b32_e32 v10, 0xffff0000, v10
	v_mul_f32_e32 v12, 0xbfb8aa3b, v25
	v_mul_f32_e32 v13, 0xbfb8aa3b, v10
	v_exp_f32_e32 v12, v12
	v_exp_f32_e32 v13, v13
	s_nop 0
	v_pk_add_f32 v[12:13], v[12:13], 1.0 op_sel_hi:[1,0]
	s_nop 0
	v_div_scale_f32 v26, s[4:5], v13, v13, v10
	v_rcp_f32_e32 v27, v26
	s_nop 0
	v_fma_f32 v28, -v26, v27, 1.0
	v_fmac_f32_e32 v27, v28, v27
	v_div_scale_f32 v28, vcc, v10, v13, v10
	v_mul_f32_e32 v29, v28, v27
	v_fma_f32 v30, -v26, v29, v28
	v_rcp_f32_e32 v26, v13
	s_nop 0
	v_mul_f32_e32 v13, v10, v26
	v_div_scale_f32 v10, s[4:5], v12, v12, v25
	v_rcp_f32_e32 v26, v10
	s_nop 0
	v_fma_f32 v27, -v10, v26, 1.0
	v_fmac_f32_e32 v26, v27, v26
	v_div_scale_f32 v27, vcc, v25, v12, v25
	v_mul_f32_e32 v28, v27, v26
	v_fma_f32 v29, -v10, v28, v27
	v_rcp_f32_e32 v10, v12
	s_nop 0
	v_mul_f32_e32 v12, v25, v10
	v_pk_mul_f32 v[6:7], v[6:7], v[12:13]
	v_and_b32_e32 v12, 0xffff0000, v11
	v_cvt_pk_bf16_f32 v6, v6, v7
	v_lshlrev_b32_e32 v7, 16, v11
	v_mul_f32_e32 v10, 0xbfb8aa3b, v7
	v_mul_f32_e32 v11, 0xbfb8aa3b, v12
	v_exp_f32_e32 v10, v10
	v_exp_f32_e32 v11, v11
	s_nop 0
	v_pk_add_f32 v[10:11], v[10:11], 1.0 op_sel_hi:[1,0]
	s_nop 0
	v_div_scale_f32 v13, s[4:5], v11, v11, v12
	v_rcp_f32_e32 v25, v13
	s_nop 0
	v_fma_f32 v26, -v13, v25, 1.0
	v_fmac_f32_e32 v25, v26, v25
	v_div_scale_f32 v26, vcc, v12, v11, v12
	v_mul_f32_e32 v27, v26, v25
	v_fma_f32 v28, -v13, v27, v26
	v_rcp_f32_e32 v13, v11
	s_nop 0
	v_mul_f32_e32 v11, v12, v13
	v_div_scale_f32 v12, s[4:5], v10, v10, v7
	v_rcp_f32_e32 v13, v12
	s_nop 0
	v_fma_f32 v25, -v12, v13, 1.0
	v_fmac_f32_e32 v13, v25, v13
	v_div_scale_f32 v25, vcc, v7, v10, v7
	v_mul_f32_e32 v26, v25, v13
	v_fma_f32 v27, -v12, v26, v25
	v_rcp_f32_e32 v12, v10
	s_nop 0
	v_mul_f32_e32 v10, v7, v12
	v_pk_mul_f32 v[8:9], v[8:9], v[10:11]
	s_nop 0
	v_cvt_pk_bf16_f32 v7, v8, v9
	v_mov_b32_e32 v8, v118
	v_mov_b32_e32 v9, v119
	s_nop 0
	v_lshlrev_b32_e32 v12, 16, v8
	v_and_b32_e32 v8, 0xffff0000, v8
	v_mul_f32_e32 v10, 0xbfb8aa3b, v12
	v_mul_f32_e32 v11, 0xbfb8aa3b, v8
	v_exp_f32_e32 v10, v10
	v_exp_f32_e32 v11, v11
	s_nop 0
	v_pk_add_f32 v[10:11], v[10:11], 1.0 op_sel_hi:[1,0]
	s_nop 0
	v_div_scale_f32 v13, s[4:5], v11, v11, v8
	v_rcp_f32_e32 v20, v13
	s_nop 0
	v_fma_f32 v21, -v13, v20, 1.0
	v_fmac_f32_e32 v20, v21, v20
	v_div_scale_f32 v21, vcc, v8, v11, v8
	v_mul_f32_e32 v25, v21, v20
	v_fma_f32 v26, -v13, v25, v21
	v_rcp_f32_e32 v13, v11
	s_nop 0
	v_mul_f32_e32 v11, v8, v13
	v_div_scale_f32 v8, s[4:5], v10, v10, v12
	v_rcp_f32_e32 v13, v8
	s_nop 0
	v_fma_f32 v20, -v8, v13, 1.0
	v_fmac_f32_e32 v13, v20, v13
	v_div_scale_f32 v20, vcc, v12, v10, v12
	v_mul_f32_e32 v21, v20, v13
	v_fma_f32 v25, -v8, v21, v20
	v_fmac_f32_e32 v21, v25, v13
	v_rcp_f32_e32 v8, v10
	s_nop 0
	v_mul_f32_e32 v10, v12, v8
	v_pk_mul_f32 v[2:3], v[2:3], v[10:11]
	v_lshlrev_b32_e32 v10, 16, v9
	v_and_b32_e32 v9, 0xffff0000, v9
	v_cvt_pk_bf16_f32 v8, v2, v3
	v_mul_f32_e32 v2, 0xbfb8aa3b, v10
	v_mul_f32_e32 v0, 0xbfb8aa3b, v9
	v_exp_f32_e32 v2, v2
	v_exp_f32_e32 v3, v0
	v_permlane16_swap_b32_e32 v6, v8
	v_pk_add_f32 v[2:3], v[2:3], 1.0 op_sel_hi:[1,0]
	s_nop 0
	v_div_scale_f32 v0, s[4:5], v3, v3, v9
	v_rcp_f32_e32 v11, v0
	s_nop 0
	v_fma_f32 v12, -v0, v11, 1.0
	v_fmac_f32_e32 v11, v12, v11
	v_div_scale_f32 v12, vcc, v9, v3, v9
	v_mul_f32_e32 v13, v12, v11
	v_fma_f32 v20, -v0, v13, v12
	v_rcp_f32_e32 v0, v3
	s_nop 0
	v_mul_f32_e32 v3, v9, v0
	v_div_scale_f32 v0, s[4:5], v2, v2, v10
	v_rcp_f32_e32 v9, v0
	s_nop 0
	v_fma_f32 v11, -v0, v9, 1.0
	v_fmac_f32_e32 v9, v11, v9
	v_div_scale_f32 v11, vcc, v10, v2, v10
	v_mul_f32_e32 v12, v11, v9
	v_fma_f32 v13, -v0, v12, v11
	v_fmac_f32_e32 v12, v13, v9
	v_rcp_f32_e32 v0, v2
	s_nop 0
	v_mul_f32_e32 v2, v10, v0
	v_pk_mul_f32 v[2:3], v[4:5], v[2:3]
	v_cmp_eq_u32_e32 vcc, 0, v22
	v_cvt_pk_bf16_f32 v9, v2, v3
	v_lshlrev_b64 v[4:5], 11, v[18:19]
	v_cndmask_b32_e32 v2, v24, v23, vcc
	v_lshl_add_u64 v[4:5], s[0:1], 0, v[4:5]
	v_ashrrev_i32_e32 v3, 31, v2
	v_lshl_add_u64 v[2:3], v[2:3], 1, v[4:5]
	v_permlane16_swap_b32_e32 v7, v9
	global_store_dwordx4 v[2:3], v[14:17], off
	global_store_dwordx4 v[2:3], v[6:9], off offset:64
	s_barrier

.LBB0_730:
	s_cmpk_lt_i32 s4, 0x400
	s_cbranch_scc0 .Lqkn_skip
	v_readlane_b32 s0, v251, 48
	v_readlane_b32 s1, v251, 49
	v_readlane_b32 s6, v251, 50
	v_readlane_b32 s7, v251, 51
	v_readlane_b32 s5, v252, 50
	s_cmpk_lt_i32 s4, 0x200
	s_cselect_b32 s0, s0, s6
	s_cselect_b32 s1, s1, s7
	s_cselect_b32 s8, 0x3e38aa3b, 1.0
	s_lshl_b32 s5, s5, 8
	s_add_u32 s0, s0, s5
	s_addc_u32 s1, s1, 0
	s_mov_b32 s9, 0x3c800000
	v_bfe_u32 v176, v175, 4, 2
	v_lshlrev_b32_e32 v176, 4, v176
	global_load_dwordx4 v[184:187], v176, s[0:1]
	global_load_dwordx4 v[188:191], v176, s[0:1] offset:64
	global_load_dwordx4 v[192:195], v176, s[0:1] offset:128
	global_load_dwordx4 v[196:199], v176, s[0:1] offset:192
	v_mul_f32_e32 v177, v170, v170
	v_fmac_f32_e32 v177, v171, v171
	v_fmac_f32_e32 v177, v172, v172
	v_fmac_f32_e32 v177, v173, v173
	v_fmac_f32_e32 v177, v166, v166
	v_fmac_f32_e32 v177, v167, v167
	v_fmac_f32_e32 v177, v168, v168
	v_fmac_f32_e32 v177, v169, v169
	v_fmac_f32_e32 v177, v162, v162
	v_fmac_f32_e32 v177, v163, v163
	v_fmac_f32_e32 v177, v164, v164
	v_fmac_f32_e32 v177, v165, v165
	v_fmac_f32_e32 v177, v158, v158
	v_fmac_f32_e32 v177, v159, v159
	v_fmac_f32_e32 v177, v160, v160
	v_fmac_f32_e32 v177, v161, v161
	v_mov_b32_e32 v178, v177
	s_nop 1
	v_permlane16_swap_b32_e32 v177, v178
	s_nop 1
	v_add_f32_e32 v177, v177, v178
	v_mov_b32_e32 v178, v177
	s_nop 1
	v_permlane32_swap_b32_e32 v177, v178
	s_nop 1
	v_add_f32_e32 v177, v177, v178
	v_fma_f32 v177, v177, s9, v240
	v_rsq_f32_e32 v50, v177
	v_mul_f32_e32 v177, v154, v154
	v_fmac_f32_e32 v177, v155, v155
	v_fmac_f32_e32 v177, v156, v156
	v_fmac_f32_e32 v177, v157, v157
	v_fmac_f32_e32 v177, v150, v150
	v_fmac_f32_e32 v177, v151, v151
	v_fmac_f32_e32 v177, v152, v152
	v_fmac_f32_e32 v177, v153, v153
	v_fmac_f32_e32 v177, v146, v146
	v_fmac_f32_e32 v177, v147, v147
	v_fmac_f32_e32 v177, v148, v148
	v_fmac_f32_e32 v177, v149, v149
	v_fmac_f32_e32 v177, v142, v142
	v_fmac_f32_e32 v177, v143, v143
	v_fmac_f32_e32 v177, v144, v144
	v_fmac_f32_e32 v177, v145, v145
	v_mov_b32_e32 v178, v177
	s_nop 1
	v_permlane16_swap_b32_e32 v177, v178
	s_nop 1
	v_add_f32_e32 v177, v177, v178
	v_mov_b32_e32 v178, v177
	s_nop 1
	v_permlane32_swap_b32_e32 v177, v178
	s_nop 1
	v_add_f32_e32 v177, v177, v178
	v_fma_f32 v177, v177, s9, v240
	v_rsq_f32_e32 v52, v177
	v_mul_f32_e32 v177, v138, v138
	v_fmac_f32_e32 v177, v139, v139
	v_fmac_f32_e32 v177, v140, v140
	v_fmac_f32_e32 v177, v141, v141
	v_fmac_f32_e32 v177, v134, v134
	v_fmac_f32_e32 v177, v135, v135
	v_fmac_f32_e32 v177, v136, v136
	v_fmac_f32_e32 v177, v137, v137
	v_fmac_f32_e32 v177, v130, v130
	v_fmac_f32_e32 v177, v131, v131
	v_fmac_f32_e32 v177, v132, v132
	v_fmac_f32_e32 v177, v133, v133
	v_fmac_f32_e32 v177, v126, v126
	v_fmac_f32_e32 v177, v127, v127
	v_fmac_f32_e32 v177, v128, v128
	v_fmac_f32_e32 v177, v129, v129
	v_mov_b32_e32 v178, v177
	s_nop 1
	v_permlane16_swap_b32_e32 v177, v178
	s_nop 1
	v_add_f32_e32 v177, v177, v178
	v_mov_b32_e32 v178, v177
	s_nop 1
	v_permlane32_swap_b32_e32 v177, v178
	s_nop 1
	v_add_f32_e32 v177, v177, v178
	v_fma_f32 v177, v177, s9, v240
	v_rsq_f32_e32 v54, v177
	v_mul_f32_e32 v177, v122, v122
	v_fmac_f32_e32 v177, v123, v123
	v_fmac_f32_e32 v177, v124, v124
	v_fmac_f32_e32 v177, v125, v125
	v_fmac_f32_e32 v177, v114, v114
	v_fmac_f32_e32 v177, v115, v115
	v_fmac_f32_e32 v177, v116, v116
	v_fmac_f32_e32 v177, v117, v117
	v_fmac_f32_e32 v177, v110, v110
	v_fmac_f32_e32 v177, v111, v111
	v_fmac_f32_e32 v177, v112, v112
	v_fmac_f32_e32 v177, v113, v113
	v_fmac_f32_e32 v177, v106, v106
	v_fmac_f32_e32 v177, v107, v107
	v_fmac_f32_e32 v177, v108, v108
	v_fmac_f32_e32 v177, v109, v109
	v_mov_b32_e32 v178, v177
	s_nop 1
	v_permlane16_swap_b32_e32 v177, v178
	s_nop 1
	v_add_f32_e32 v177, v177, v178
	v_mov_b32_e32 v178, v177
	s_nop 1
	v_permlane32_swap_b32_e32 v177, v178
	s_nop 1
	v_add_f32_e32 v177, v177, v178
	v_fma_f32 v177, v177, s9, v240
	v_rsq_f32_e32 v56, v177
	v_mul_f32_e32 v177, v98, v98
	v_fmac_f32_e32 v177, v99, v99
	v_fmac_f32_e32 v177, v100, v100
	v_fmac_f32_e32 v177, v101, v101
	v_fmac_f32_e32 v177, v94, v94
	v_fmac_f32_e32 v177, v95, v95
	v_fmac_f32_e32 v177, v96, v96
	v_fmac_f32_e32 v177, v97, v97
	v_fmac_f32_e32 v177, v90, v90
	v_fmac_f32_e32 v177, v91, v91
	v_fmac_f32_e32 v177, v92, v92
	v_fmac_f32_e32 v177, v93, v93
	v_fmac_f32_e32 v177, v86, v86
	v_fmac_f32_e32 v177, v87, v87
	v_fmac_f32_e32 v177, v88, v88
	v_fmac_f32_e32 v177, v89, v89
	v_mov_b32_e32 v178, v177
	s_nop 1
	v_permlane16_swap_b32_e32 v177, v178
	s_nop 1
	v_add_f32_e32 v177, v177, v178
	v_mov_b32_e32 v178, v177
	s_nop 1
	v_permlane32_swap_b32_e32 v177, v178
	s_nop 1
	v_add_f32_e32 v177, v177, v178
	v_fma_f32 v177, v177, s9, v240
	v_rsq_f32_e32 v66, v177
	v_mul_f32_e32 v177, v82, v82
	v_fmac_f32_e32 v177, v83, v83
	v_fmac_f32_e32 v177, v84, v84
	v_fmac_f32_e32 v177, v85, v85
	v_fmac_f32_e32 v177, v78, v78
	v_fmac_f32_e32 v177, v79, v79
	v_fmac_f32_e32 v177, v80, v80
	v_fmac_f32_e32 v177, v81, v81
	v_fmac_f32_e32 v177, v62, v62
	v_fmac_f32_e32 v177, v63, v63
	v_fmac_f32_e32 v177, v64, v64
	v_fmac_f32_e32 v177, v65, v65
	v_fmac_f32_e32 v177, v58, v58
	v_fmac_f32_e32 v177, v59, v59
	v_fmac_f32_e32 v177, v60, v60
	v_fmac_f32_e32 v177, v61, v61
	v_mov_b32_e32 v178, v177
	s_nop 1
	v_permlane16_swap_b32_e32 v177, v178
	s_nop 1
	v_add_f32_e32 v177, v177, v178
	v_mov_b32_e32 v178, v177
	s_nop 1
	v_permlane32_swap_b32_e32 v177, v178
	s_nop 1
	v_add_f32_e32 v177, v177, v178
	v_fma_f32 v177, v177, s9, v240
	v_rsq_f32_e32 v68, v177
	v_mul_f32_e32 v177, v46, v46
	v_fmac_f32_e32 v177, v47, v47
	v_fmac_f32_e32 v177, v48, v48
	v_fmac_f32_e32 v177, v49, v49
	v_fmac_f32_e32 v177, v42, v42
	v_fmac_f32_e32 v177, v43, v43
	v_fmac_f32_e32 v177, v44, v44
	v_fmac_f32_e32 v177, v45, v45
	v_fmac_f32_e32 v177, v38, v38
	v_fmac_f32_e32 v177, v39, v39
	v_fmac_f32_e32 v177, v40, v40
	v_fmac_f32_e32 v177, v41, v41
	v_fmac_f32_e32 v177, v34, v34
	v_fmac_f32_e32 v177, v35, v35
	v_fmac_f32_e32 v177, v36, v36
	v_fmac_f32_e32 v177, v37, v37
	v_mov_b32_e32 v178, v177
	s_nop 1
	v_permlane16_swap_b32_e32 v177, v178
	s_nop 1
	v_add_f32_e32 v177, v177, v178
	v_mov_b32_e32 v178, v177
	s_nop 1
	v_permlane32_swap_b32_e32 v177, v178
	s_nop 1
	v_add_f32_e32 v177, v177, v178
	v_fma_f32 v177, v177, s9, v240
	v_rsq_f32_e32 v70, v177
	v_mul_f32_e32 v177, v30, v30
	v_fmac_f32_e32 v177, v31, v31
	v_fmac_f32_e32 v177, v32, v32
	v_fmac_f32_e32 v177, v33, v33
	v_fmac_f32_e32 v177, v26, v26
	v_fmac_f32_e32 v177, v27, v27
	v_fmac_f32_e32 v177, v28, v28
	v_fmac_f32_e32 v177, v29, v29
	v_fmac_f32_e32 v177, v22, v22
	v_fmac_f32_e32 v177, v23, v23
	v_fmac_f32_e32 v177, v24, v24
	v_fmac_f32_e32 v177, v25, v25
	v_fmac_f32_e32 v177, v18, v18
	v_fmac_f32_e32 v177, v19, v19
	v_fmac_f32_e32 v177, v20, v20
	v_fmac_f32_e32 v177, v21, v21
	v_mov_b32_e32 v178, v177
	s_nop 1
	v_permlane16_swap_b32_e32 v177, v178
	s_nop 1
	v_add_f32_e32 v177, v177, v178
	v_mov_b32_e32 v178, v177
	s_nop 1
	v_permlane32_swap_b32_e32 v177, v178
	s_nop 1
	v_add_f32_e32 v177, v177, v178
	v_fma_f32 v177, v177, s9, v240
	v_rsq_f32_e32 v72, v177
	v_mul_f32_e32 v177, v14, v14
	v_fmac_f32_e32 v177, v15, v15
	v_fmac_f32_e32 v177, v16, v16
	v_fmac_f32_e32 v177, v17, v17
	v_fmac_f32_e32 v177, v10, v10
	v_fmac_f32_e32 v177, v11, v11
	v_fmac_f32_e32 v177, v12, v12
	v_fmac_f32_e32 v177, v13, v13
	v_fmac_f32_e32 v177, v6, v6
	v_fmac_f32_e32 v177, v7, v7
	v_fmac_f32_e32 v177, v8, v8
	v_fmac_f32_e32 v177, v9, v9
	v_fmac_f32_e32 v177, v2, v2
	v_fmac_f32_e32 v177, v3, v3
	v_fmac_f32_e32 v177, v4, v4
	v_fmac_f32_e32 v177, v5, v5
	v_mov_b32_e32 v178, v177
	s_nop 1
	v_permlane16_swap_b32_e32 v177, v178
	s_nop 1
	v_add_f32_e32 v177, v177, v178
	v_mov_b32_e32 v178, v177
	s_nop 1
	v_permlane32_swap_b32_e32 v177, v178
	s_nop 1
	v_add_f32_e32 v177, v177, v178
	v_fma_f32 v177, v177, s9, v240
	v_rsq_f32_e32 v74, v177
	s_waitcnt vmcnt(0)
	v_mul_f32_e32 v184, s8, v184
	v_mul_f32_e32 v185, s8, v185
	v_mul_f32_e32 v186, s8, v186
	v_mul_f32_e32 v187, s8, v187
	v_mul_f32_e32 v188, s8, v188
	v_mul_f32_e32 v189, s8, v189
	v_mul_f32_e32 v190, s8, v190
	v_mul_f32_e32 v191, s8, v191
	v_mul_f32_e32 v192, s8, v192
	v_mul_f32_e32 v193, s8, v193
	v_mul_f32_e32 v194, s8, v194
	v_mul_f32_e32 v195, s8, v195
	v_mul_f32_e32 v196, s8, v196
	v_mul_f32_e32 v197, s8, v197
	v_mul_f32_e32 v198, s8, v198
	v_mul_f32_e32 v199, s8, v199
	v_pk_mul_f32 v[170:171], v[50:51], v[170:171] op_sel_hi:[0,1]
	v_pk_mul_f32 v[172:173], v[50:51], v[172:173] op_sel_hi:[0,1]
	v_pk_mul_f32 v[170:171], v[184:185], v[170:171]
	v_pk_mul_f32 v[172:173], v[186:187], v[172:173]
	v_pk_mul_f32 v[166:167], v[50:51], v[166:167] op_sel_hi:[0,1]
	v_pk_mul_f32 v[168:169], v[50:51], v[168:169] op_sel_hi:[0,1]
	v_pk_mul_f32 v[166:167], v[188:189], v[166:167]
	v_pk_mul_f32 v[168:169], v[190:191], v[168:169]
	v_pk_mul_f32 v[162:163], v[50:51], v[162:163] op_sel_hi:[0,1]
	v_pk_mul_f32 v[164:165], v[50:51], v[164:165] op_sel_hi:[0,1]
	v_pk_mul_f32 v[162:163], v[192:193], v[162:163]
	v_pk_mul_f32 v[164:165], v[194:195], v[164:165]
	v_pk_mul_f32 v[158:159], v[50:51], v[158:159] op_sel_hi:[0,1]
	v_pk_mul_f32 v[160:161], v[50:51], v[160:161] op_sel_hi:[0,1]
	v_pk_mul_f32 v[158:159], v[196:197], v[158:159]
	v_pk_mul_f32 v[160:161], v[198:199], v[160:161]
	v_pk_mul_f32 v[154:155], v[52:53], v[154:155] op_sel_hi:[0,1]
	v_pk_mul_f32 v[156:157], v[52:53], v[156:157] op_sel_hi:[0,1]
	v_pk_mul_f32 v[154:155], v[184:185], v[154:155]
	v_pk_mul_f32 v[156:157], v[186:187], v[156:157]
	v_pk_mul_f32 v[150:151], v[52:53], v[150:151] op_sel_hi:[0,1]
	v_pk_mul_f32 v[152:153], v[52:53], v[152:153] op_sel_hi:[0,1]
	v_pk_mul_f32 v[150:151], v[188:189], v[150:151]
	v_pk_mul_f32 v[152:153], v[190:191], v[152:153]
	v_pk_mul_f32 v[146:147], v[52:53], v[146:147] op_sel_hi:[0,1]
	v_pk_mul_f32 v[148:149], v[52:53], v[148:149] op_sel_hi:[0,1]
	v_pk_mul_f32 v[146:147], v[192:193], v[146:147]
	v_pk_mul_f32 v[148:149], v[194:195], v[148:149]
	v_pk_mul_f32 v[142:143], v[52:53], v[142:143] op_sel_hi:[0,1]
	v_pk_mul_f32 v[144:145], v[52:53], v[144:145] op_sel_hi:[0,1]
	v_pk_mul_f32 v[142:143], v[196:197], v[142:143]
	v_pk_mul_f32 v[144:145], v[198:199], v[144:145]
	v_pk_mul_f32 v[138:139], v[54:55], v[138:139] op_sel_hi:[0,1]
	v_pk_mul_f32 v[140:141], v[54:55], v[140:141] op_sel_hi:[0,1]
	v_pk_mul_f32 v[138:139], v[184:185], v[138:139]
	v_pk_mul_f32 v[140:141], v[186:187], v[140:141]
	v_pk_mul_f32 v[134:135], v[54:55], v[134:135] op_sel_hi:[0,1]
	v_pk_mul_f32 v[136:137], v[54:55], v[136:137] op_sel_hi:[0,1]
	v_pk_mul_f32 v[134:135], v[188:189], v[134:135]
	v_pk_mul_f32 v[136:137], v[190:191], v[136:137]
	v_pk_mul_f32 v[130:131], v[54:55], v[130:131] op_sel_hi:[0,1]
	v_pk_mul_f32 v[132:133], v[54:55], v[132:133] op_sel_hi:[0,1]
	v_pk_mul_f32 v[130:131], v[192:193], v[130:131]
	v_pk_mul_f32 v[132:133], v[194:195], v[132:133]
	v_pk_mul_f32 v[126:127], v[54:55], v[126:127] op_sel_hi:[0,1]
	v_pk_mul_f32 v[128:129], v[54:55], v[128:129] op_sel_hi:[0,1]
	v_pk_mul_f32 v[126:127], v[196:197], v[126:127]
	v_pk_mul_f32 v[128:129], v[198:199], v[128:129]
	v_pk_mul_f32 v[122:123], v[56:57], v[122:123] op_sel_hi:[0,1]
	v_pk_mul_f32 v[124:125], v[56:57], v[124:125] op_sel_hi:[0,1]
	v_pk_mul_f32 v[122:123], v[184:185], v[122:123]
	v_pk_mul_f32 v[124:125], v[186:187], v[124:125]
	v_pk_mul_f32 v[114:115], v[56:57], v[114:115] op_sel_hi:[0,1]
	v_pk_mul_f32 v[116:117], v[56:57], v[116:117] op_sel_hi:[0,1]
	v_pk_mul_f32 v[114:115], v[188:189], v[114:115]
	v_pk_mul_f32 v[116:117], v[190:191], v[116:117]
	v_pk_mul_f32 v[110:111], v[56:57], v[110:111] op_sel_hi:[0,1]
	v_pk_mul_f32 v[112:113], v[56:57], v[112:113] op_sel_hi:[0,1]
	v_pk_mul_f32 v[110:111], v[192:193], v[110:111]
	v_pk_mul_f32 v[112:113], v[194:195], v[112:113]
	v_pk_mul_f32 v[106:107], v[56:57], v[106:107] op_sel_hi:[0,1]
	v_pk_mul_f32 v[108:109], v[56:57], v[108:109] op_sel_hi:[0,1]
	v_pk_mul_f32 v[106:107], v[196:197], v[106:107]
	v_pk_mul_f32 v[108:109], v[198:199], v[108:109]
	v_pk_mul_f32 v[98:99], v[66:67], v[98:99] op_sel_hi:[0,1]
	v_pk_mul_f32 v[100:101], v[66:67], v[100:101] op_sel_hi:[0,1]
	v_pk_mul_f32 v[98:99], v[184:185], v[98:99]
	v_pk_mul_f32 v[100:101], v[186:187], v[100:101]
	v_pk_mul_f32 v[94:95], v[66:67], v[94:95] op_sel_hi:[0,1]
	v_pk_mul_f32 v[96:97], v[66:67], v[96:97] op_sel_hi:[0,1]
	v_pk_mul_f32 v[94:95], v[188:189], v[94:95]
	v_pk_mul_f32 v[96:97], v[190:191], v[96:97]
	v_pk_mul_f32 v[90:91], v[66:67], v[90:91] op_sel_hi:[0,1]
	v_pk_mul_f32 v[92:93], v[66:67], v[92:93] op_sel_hi:[0,1]
	v_pk_mul_f32 v[90:91], v[192:193], v[90:91]
	v_pk_mul_f32 v[92:93], v[194:195], v[92:93]
	v_pk_mul_f32 v[86:87], v[66:67], v[86:87] op_sel_hi:[0,1]
	v_pk_mul_f32 v[88:89], v[66:67], v[88:89] op_sel_hi:[0,1]
	v_pk_mul_f32 v[86:87], v[196:197], v[86:87]
	v_pk_mul_f32 v[88:89], v[198:199], v[88:89]
	v_pk_mul_f32 v[82:83], v[68:69], v[82:83] op_sel_hi:[0,1]
	v_pk_mul_f32 v[84:85], v[68:69], v[84:85] op_sel_hi:[0,1]
	v_pk_mul_f32 v[82:83], v[184:185], v[82:83]
	v_pk_mul_f32 v[84:85], v[186:187], v[84:85]
	v_pk_mul_f32 v[78:79], v[68:69], v[78:79] op_sel_hi:[0,1]
	v_pk_mul_f32 v[80:81], v[68:69], v[80:81] op_sel_hi:[0,1]
	v_pk_mul_f32 v[78:79], v[188:189], v[78:79]
	v_pk_mul_f32 v[80:81], v[190:191], v[80:81]
	v_pk_mul_f32 v[62:63], v[68:69], v[62:63] op_sel_hi:[0,1]
	v_pk_mul_f32 v[64:65], v[68:69], v[64:65] op_sel_hi:[0,1]
	v_pk_mul_f32 v[62:63], v[192:193], v[62:63]
	v_pk_mul_f32 v[64:65], v[194:195], v[64:65]
	v_pk_mul_f32 v[58:59], v[68:69], v[58:59] op_sel_hi:[0,1]
	v_pk_mul_f32 v[60:61], v[68:69], v[60:61] op_sel_hi:[0,1]
	v_pk_mul_f32 v[58:59], v[196:197], v[58:59]
	v_pk_mul_f32 v[60:61], v[198:199], v[60:61]
	v_pk_mul_f32 v[46:47], v[70:71], v[46:47] op_sel_hi:[0,1]
	v_pk_mul_f32 v[48:49], v[70:71], v[48:49] op_sel_hi:[0,1]
	v_pk_mul_f32 v[46:47], v[184:185], v[46:47]
	v_pk_mul_f32 v[48:49], v[186:187], v[48:49]
	v_pk_mul_f32 v[42:43], v[70:71], v[42:43] op_sel_hi:[0,1]
	v_pk_mul_f32 v[44:45], v[70:71], v[44:45] op_sel_hi:[0,1]
	v_pk_mul_f32 v[42:43], v[188:189], v[42:43]
	v_pk_mul_f32 v[44:45], v[190:191], v[44:45]
	v_pk_mul_f32 v[38:39], v[70:71], v[38:39] op_sel_hi:[0,1]
	v_pk_mul_f32 v[40:41], v[70:71], v[40:41] op_sel_hi:[0,1]
	v_pk_mul_f32 v[38:39], v[192:193], v[38:39]
	v_pk_mul_f32 v[40:41], v[194:195], v[40:41]
	v_pk_mul_f32 v[34:35], v[70:71], v[34:35] op_sel_hi:[0,1]
	v_pk_mul_f32 v[36:37], v[70:71], v[36:37] op_sel_hi:[0,1]
	v_pk_mul_f32 v[34:35], v[196:197], v[34:35]
	v_pk_mul_f32 v[36:37], v[198:199], v[36:37]
	v_pk_mul_f32 v[30:31], v[72:73], v[30:31] op_sel_hi:[0,1]
	v_pk_mul_f32 v[32:33], v[72:73], v[32:33] op_sel_hi:[0,1]
	v_pk_mul_f32 v[30:31], v[184:185], v[30:31]
	v_pk_mul_f32 v[32:33], v[186:187], v[32:33]
	v_pk_mul_f32 v[26:27], v[72:73], v[26:27] op_sel_hi:[0,1]
	v_pk_mul_f32 v[28:29], v[72:73], v[28:29] op_sel_hi:[0,1]
	v_pk_mul_f32 v[26:27], v[188:189], v[26:27]
	v_pk_mul_f32 v[28:29], v[190:191], v[28:29]
	v_pk_mul_f32 v[22:23], v[72:73], v[22:23] op_sel_hi:[0,1]
	v_pk_mul_f32 v[24:25], v[72:73], v[24:25] op_sel_hi:[0,1]
	v_pk_mul_f32 v[22:23], v[192:193], v[22:23]
	v_pk_mul_f32 v[24:25], v[194:195], v[24:25]
	v_pk_mul_f32 v[18:19], v[72:73], v[18:19] op_sel_hi:[0,1]
	v_pk_mul_f32 v[20:21], v[72:73], v[20:21] op_sel_hi:[0,1]
	v_pk_mul_f32 v[18:19], v[196:197], v[18:19]
	v_pk_mul_f32 v[20:21], v[198:199], v[20:21]
	v_pk_mul_f32 v[14:15], v[74:75], v[14:15] op_sel_hi:[0,1]
	v_pk_mul_f32 v[16:17], v[74:75], v[16:17] op_sel_hi:[0,1]
	v_pk_mul_f32 v[14:15], v[184:185], v[14:15]
	v_pk_mul_f32 v[16:17], v[186:187], v[16:17]
	v_pk_mul_f32 v[10:11], v[74:75], v[10:11] op_sel_hi:[0,1]
	v_pk_mul_f32 v[12:13], v[74:75], v[12:13] op_sel_hi:[0,1]
	v_pk_mul_f32 v[10:11], v[188:189], v[10:11]
	v_pk_mul_f32 v[12:13], v[190:191], v[12:13]
	v_pk_mul_f32 v[6:7], v[74:75], v[6:7] op_sel_hi:[0,1]
	v_pk_mul_f32 v[8:9], v[74:75], v[8:9] op_sel_hi:[0,1]
	v_pk_mul_f32 v[6:7], v[192:193], v[6:7]
	v_pk_mul_f32 v[8:9], v[194:195], v[8:9]
	v_pk_mul_f32 v[2:3], v[74:75], v[2:3] op_sel_hi:[0,1]
	v_pk_mul_f32 v[4:5], v[74:75], v[4:5] op_sel_hi:[0,1]
	v_pk_mul_f32 v[2:3], v[196:197], v[2:3]
	v_pk_mul_f32 v[4:5], v[198:199], v[4:5]
